# in-proj GEMM uses 44 column tiles for all layers; the 48 stray value-residual columns computed by a per-workgroup MFMA block at the end of the phase; plus rstd_table load pipelining and PRM load overl
# baseline (speedup 1.0000x reference)
; #define GAS __attribute__((address_space(1)))
; #define SB() __builtin_amdgcn_sched_barrier(0)
; DI const LAS float* rstd_table(const Frame& F) {
;     ...
;     for (int r = F.tid; r < 2048; r += 512) { f32x4 p[8];
; #pragma unroll
;         for (int q = 0; q < 8; ++q) p[q] = ((const GAS f32x4*)(P + (size_t)r * 32))[q];
;         SB();
;         f32x4 t = (p[0] + p[1]) + (p[2] + p[3]) + ((p[4] + p[5]) + (p[6] + p[7]));
;         tab[r] = 1.f / sqrtf(((t[0] + t[1]) + (t[2] + t[3])) * (1.f / D) + NORM_EPS);
;         SB(); }
.LBB0_366:
	v_lshl_add_u64 v[132:133], v[0:1], 0, s[16:17]
	v_lshl_add_u64 v[134:135], v[132:133], 0, s[16:17]
	v_lshl_add_u64 v[136:137], v[134:135], 0, s[16:17]
	global_load_dwordx4 v[4:7], v[0:1], off offset:32
	global_load_dwordx4 v[8:11], v[0:1], off offset:48
	global_load_dwordx4 v[12:15], v[0:1], off
	global_load_dwordx4 v[16:19], v[0:1], off offset:16
	global_load_dwordx4 v[20:23], v[0:1], off offset:96
	global_load_dwordx4 v[24:27], v[0:1], off offset:112
	global_load_dwordx4 v[28:31], v[0:1], off offset:64
	global_load_dwordx4 v[32:35], v[0:1], off offset:80
	global_load_dwordx4 v[36:39], v[132:133], off offset:32
	global_load_dwordx4 v[40:43], v[132:133], off offset:48
	global_load_dwordx4 v[44:47], v[132:133], off
	global_load_dwordx4 v[48:51], v[132:133], off offset:16
	global_load_dwordx4 v[52:55], v[132:133], off offset:96
	global_load_dwordx4 v[56:59], v[132:133], off offset:112
	global_load_dwordx4 v[60:63], v[132:133], off offset:64
	global_load_dwordx4 v[64:67], v[132:133], off offset:80
	global_load_dwordx4 v[68:71], v[134:135], off offset:32
	global_load_dwordx4 v[72:75], v[134:135], off offset:48
	global_load_dwordx4 v[76:79], v[134:135], off
	global_load_dwordx4 v[80:83], v[134:135], off offset:16
	global_load_dwordx4 v[84:87], v[134:135], off offset:96
	global_load_dwordx4 v[88:91], v[134:135], off offset:112
	global_load_dwordx4 v[92:95], v[134:135], off offset:64
	global_load_dwordx4 v[96:99], v[134:135], off offset:80
	global_load_dwordx4 v[100:103], v[136:137], off offset:32
	global_load_dwordx4 v[104:107], v[136:137], off offset:48
	global_load_dwordx4 v[108:111], v[136:137], off
	global_load_dwordx4 v[112:115], v[136:137], off offset:16
	global_load_dwordx4 v[116:119], v[136:137], off offset:96
	global_load_dwordx4 v[120:123], v[136:137], off offset:112
	global_load_dwordx4 v[124:127], v[136:137], off offset:64
	global_load_dwordx4 v[128:131], v[136:137], off offset:80
	s_waitcnt vmcnt(28)
	v_pk_add_f32 v[14:15], v[14:15], v[18:19]
	v_pk_add_f32 v[12:13], v[12:13], v[16:17]
	v_pk_add_f32 v[6:7], v[6:7], v[10:11]
	v_pk_add_f32 v[4:5], v[4:5], v[8:9]
	v_pk_add_f32 v[6:7], v[14:15], v[6:7]
	v_pk_add_f32 v[4:5], v[12:13], v[4:5]
	s_waitcnt vmcnt(24)
	v_pk_add_f32 v[8:9], v[30:31], v[34:35]
	v_pk_add_f32 v[10:11], v[28:29], v[32:33]
	v_pk_add_f32 v[12:13], v[22:23], v[26:27]
	v_pk_add_f32 v[14:15], v[20:21], v[24:25]
	v_pk_add_f32 v[8:9], v[8:9], v[12:13]
	v_pk_add_f32 v[10:11], v[10:11], v[14:15]
	v_pk_add_f32 v[6:7], v[6:7], v[8:9]
	v_pk_add_f32 v[4:5], v[4:5], v[10:11]
	s_nop 0
	v_pk_mov_b32 v[8:9], v[4:5], v[6:7] op_sel:[1,0]
	v_mov_b32_e32 v5, v7
	v_pk_add_f32 v[4:5], v[8:9], v[4:5]
	s_nop 0
	v_add_f32_e32 v4, v4, v5
	v_fmamk_f32 v4, v4, 0x3a000000, v225
	v_mul_f32_e32 v5, 0x4f800000, v4
	v_cmp_gt_f32_e32 vcc, s14, v4
	s_nop 1
	v_cndmask_b32_e32 v4, v4, v5, vcc
	v_sqrt_f32_e32 v5, v4
	s_nop 0
	v_add_u32_e32 v6, -1, v5
	v_fma_f32 v7, -v6, v5, v4
	v_cmp_ge_f32_e64 s[4:5], 0, v7
	v_add_u32_e32 v7, 1, v5
	s_nop 0
	v_cndmask_b32_e64 v6, v5, v6, s[4:5]
	v_fma_f32 v5, -v7, v5, v4
	v_cmp_lt_f32_e64 s[4:5], 0, v5
	s_nop 1
	v_cndmask_b32_e64 v5, v6, v7, s[4:5]
	v_mul_f32_e32 v6, 0x37800000, v5
	v_cndmask_b32_e32 v5, v5, v6, vcc
	v_cmp_class_f32_e32 vcc, v4, v226
	s_nop 1
	v_cndmask_b32_e32 v4, v5, v4, vcc
	v_div_scale_f32 v5, s[0:1], v4, v4, 1.0
	v_rcp_f32_e32 v6, v5
	s_nop 0
	v_fma_f32 v7, -v5, v6, 1.0
	v_fmac_f32_e32 v6, v7, v6
	v_div_scale_f32 v7, vcc, 1.0, v4, 1.0
	v_mul_f32_e32 v8, v7, v6
	v_fma_f32 v9, -v5, v8, v7
	v_fmac_f32_e32 v8, v9, v6
	v_fma_f32 v5, -v5, v8, v7
	v_div_fmas_f32 v5, v5, v6, v8
	v_div_fixup_f32 v4, v5, v4, 1.0
	ds_write_b32 v3, v4
	s_waitcnt vmcnt(20)
	v_pk_add_f32 v[46:47], v[46:47], v[50:51]
	v_pk_add_f32 v[44:45], v[44:45], v[48:49]
	v_pk_add_f32 v[38:39], v[38:39], v[42:43]
	v_pk_add_f32 v[36:37], v[36:37], v[40:41]
	v_pk_add_f32 v[38:39], v[46:47], v[38:39]
	v_pk_add_f32 v[36:37], v[44:45], v[36:37]
	s_waitcnt vmcnt(16)
	v_pk_add_f32 v[40:41], v[62:63], v[66:67]
	v_pk_add_f32 v[42:43], v[60:61], v[64:65]
	v_pk_add_f32 v[44:45], v[54:55], v[58:59]
	v_pk_add_f32 v[46:47], v[52:53], v[56:57]
	v_pk_add_f32 v[40:41], v[40:41], v[44:45]
	v_pk_add_f32 v[42:43], v[42:43], v[46:47]
	v_pk_add_f32 v[38:39], v[38:39], v[40:41]
	v_pk_add_f32 v[36:37], v[36:37], v[42:43]
	s_nop 0
	v_pk_mov_b32 v[40:41], v[36:37], v[38:39] op_sel:[1,0]
	v_mov_b32_e32 v37, v39
	v_pk_add_f32 v[36:37], v[40:41], v[36:37]
	s_nop 0
	v_add_f32_e32 v36, v36, v37
	v_fmamk_f32 v36, v36, 0x3a000000, v225
	v_mul_f32_e32 v37, 0x4f800000, v36
	v_cmp_gt_f32_e32 vcc, s14, v36
	s_nop 1
	v_cndmask_b32_e32 v36, v36, v37, vcc
	v_sqrt_f32_e32 v37, v36
	s_nop 0
	v_add_u32_e32 v38, -1, v37
	v_fma_f32 v39, -v38, v37, v36
	v_cmp_ge_f32_e64 s[4:5], 0, v39
	v_add_u32_e32 v39, 1, v37
	s_nop 0
	v_cndmask_b32_e64 v38, v37, v38, s[4:5]
	v_fma_f32 v37, -v39, v37, v36
	v_cmp_lt_f32_e64 s[4:5], 0, v37
	s_nop 1
	v_cndmask_b32_e64 v37, v38, v39, s[4:5]
	v_mul_f32_e32 v38, 0x37800000, v37
	v_cndmask_b32_e32 v37, v37, v38, vcc
	v_cmp_class_f32_e32 vcc, v36, v226
	s_nop 1
	v_cndmask_b32_e32 v36, v37, v36, vcc
	v_div_scale_f32 v37, s[0:1], v36, v36, 1.0
	v_rcp_f32_e32 v38, v37
	s_nop 0
	v_fma_f32 v39, -v37, v38, 1.0
	v_fmac_f32_e32 v38, v39, v38
	v_div_scale_f32 v39, vcc, 1.0, v36, 1.0
	v_mul_f32_e32 v40, v39, v38
	v_fma_f32 v41, -v37, v40, v39
	v_fmac_f32_e32 v40, v41, v38
	v_fma_f32 v37, -v37, v40, v39
	v_div_fmas_f32 v37, v37, v38, v40
	v_div_fixup_f32 v36, v37, v36, 1.0
	ds_write_b32 v3, v36 offset:2048
	s_waitcnt vmcnt(12)
; #define GAS __attribute__((address_space(1)))
; #define LAS __attribute__((address_space(3)))
;     DI void init(const bf16* A_, int lda, const bf16* B_, int ldb, int nM, int nN, int K, int G_, int c_) { T.init(nM, nN); G = G_; c = c_; nt = K / BK; A = (const char*)A_; B = (const char*)B_; ta = (size_t)BM * lda * 2; tb = (size_t)BM * ldb * 2; }
;     DI void init(const bf16* A_, int lda, const bf16* B_, int ldb, int nM, int nN, int G_, int c_) { T.init(nM, nN); G = G_; c = c_; A = (const char*)A_; B = (const char*)B_; ta = (size_t)BM * lda * 2; tb = (size_t)BM * ldb * 2; }
; #define SB() __builtin_amdgcn_sched_barrier(0)
; DI const LAS float* rstd_table(const Frame& F) {
;     ...
;     for (int r = F.tid; r < 2048; r += 512) { f32x4 p[8];
; #pragma unroll
;         for (int q = 0; q < 8; ++q) p[q] = ((const GAS f32x4*)(P + (size_t)r * 32))[q];
;         SB();
;         f32x4 t = (p[0] + p[1]) + (p[2] + p[3]) + ((p[4] + p[5]) + (p[6] + p[7]));
;         tab[r] = 1.f / sqrtf(((t[0] + t[1]) + (t[2] + t[3])) * (1.f / D) + NORM_EPS);
;         SB(); }
; __global__ void __launch_bounds__(512, 2) trunk_fwd(Args args_unused) {
;     ...
;             const int nN = (l == 0) ? 44 : 45;
;             const LAS float* rs = rstd_table(F);
;             SchedPlain S; S.init((const bf16*)F.out, XP, (const bf16*)lw(F, l, LW_WIN), D, M / BM, nN, D, F.G, F.bid);
;             EpiInproj E{(bf16*)(F.ws + WS_R2), A.in[3] + (size_t)l * 6144, (bf16*)(F.ws + WS_ZS5), rs};
;             gemm_phase<EpiInproj, SchedPlain>(F.lds, F.wave, XP, D, S, E);
	v_pk_add_f32 v[78:79], v[78:79], v[82:83]
	v_pk_add_f32 v[76:77], v[76:77], v[80:81]
	v_pk_add_f32 v[70:71], v[70:71], v[74:75]
	v_pk_add_f32 v[68:69], v[68:69], v[72:73]
	v_pk_add_f32 v[70:71], v[78:79], v[70:71]
	v_pk_add_f32 v[68:69], v[76:77], v[68:69]
	s_waitcnt vmcnt(8)
	v_pk_add_f32 v[72:73], v[94:95], v[98:99]
	v_pk_add_f32 v[74:75], v[92:93], v[96:97]
	v_pk_add_f32 v[76:77], v[86:87], v[90:91]
	v_pk_add_f32 v[78:79], v[84:85], v[88:89]
	v_pk_add_f32 v[72:73], v[72:73], v[76:77]
	v_pk_add_f32 v[74:75], v[74:75], v[78:79]
	v_pk_add_f32 v[70:71], v[70:71], v[72:73]
	v_pk_add_f32 v[68:69], v[68:69], v[74:75]
	s_nop 0
	v_pk_mov_b32 v[72:73], v[68:69], v[70:71] op_sel:[1,0]
	v_mov_b32_e32 v69, v71
	v_pk_add_f32 v[68:69], v[72:73], v[68:69]
	s_nop 0
	v_add_f32_e32 v68, v68, v69
	v_fmamk_f32 v68, v68, 0x3a000000, v225
	v_mul_f32_e32 v69, 0x4f800000, v68
	v_cmp_gt_f32_e32 vcc, s14, v68
	s_nop 1
	v_cndmask_b32_e32 v68, v68, v69, vcc
	v_sqrt_f32_e32 v69, v68
	s_nop 0
	v_add_u32_e32 v70, -1, v69
	v_fma_f32 v71, -v70, v69, v68
	v_cmp_ge_f32_e64 s[4:5], 0, v71
	v_add_u32_e32 v71, 1, v69
	s_nop 0
	v_cndmask_b32_e64 v70, v69, v70, s[4:5]
	v_fma_f32 v69, -v71, v69, v68
	v_cmp_lt_f32_e64 s[4:5], 0, v69
	s_nop 1
	v_cndmask_b32_e64 v69, v70, v71, s[4:5]
	v_mul_f32_e32 v70, 0x37800000, v69
	v_cndmask_b32_e32 v69, v69, v70, vcc
	v_cmp_class_f32_e32 vcc, v68, v226
	s_nop 1
	v_cndmask_b32_e32 v68, v69, v68, vcc
	v_div_scale_f32 v69, s[0:1], v68, v68, 1.0
	v_rcp_f32_e32 v70, v69
	s_nop 0
	v_fma_f32 v71, -v69, v70, 1.0
	v_fmac_f32_e32 v70, v71, v70
	v_div_scale_f32 v71, vcc, 1.0, v68, 1.0
	v_mul_f32_e32 v72, v71, v70
	v_fma_f32 v73, -v69, v72, v71
	v_fmac_f32_e32 v72, v73, v70
	v_fma_f32 v69, -v69, v72, v71
	v_div_fmas_f32 v69, v69, v70, v72
	v_div_fixup_f32 v68, v69, v68, 1.0
	ds_write_b32 v3, v68 offset:4096
	s_waitcnt vmcnt(4)
	v_pk_add_f32 v[110:111], v[110:111], v[114:115]
	v_pk_add_f32 v[108:109], v[108:109], v[112:113]
	v_pk_add_f32 v[102:103], v[102:103], v[106:107]
	v_pk_add_f32 v[100:101], v[100:101], v[104:105]
	v_pk_add_f32 v[102:103], v[110:111], v[102:103]
	v_pk_add_f32 v[100:101], v[108:109], v[100:101]
	s_waitcnt vmcnt(0)
	v_pk_add_f32 v[104:105], v[126:127], v[130:131]
	v_pk_add_f32 v[106:107], v[124:125], v[128:129]
	v_pk_add_f32 v[108:109], v[118:119], v[122:123]
	v_pk_add_f32 v[110:111], v[116:117], v[120:121]
	v_pk_add_f32 v[104:105], v[104:105], v[108:109]
	v_pk_add_f32 v[106:107], v[106:107], v[110:111]
	v_pk_add_f32 v[102:103], v[102:103], v[104:105]
	v_pk_add_f32 v[100:101], v[100:101], v[106:107]
	s_nop 0
	v_pk_mov_b32 v[104:105], v[100:101], v[102:103] op_sel:[1,0]
	v_mov_b32_e32 v101, v103
	v_pk_add_f32 v[100:101], v[104:105], v[100:101]
	s_nop 0
	v_add_f32_e32 v100, v100, v101
	v_fmamk_f32 v100, v100, 0x3a000000, v225
	v_mul_f32_e32 v101, 0x4f800000, v100
	v_cmp_gt_f32_e32 vcc, s14, v100
	s_nop 1
	v_cndmask_b32_e32 v100, v100, v101, vcc
	v_sqrt_f32_e32 v101, v100
	s_nop 0
	v_add_u32_e32 v102, -1, v101
	v_fma_f32 v103, -v102, v101, v100
	v_cmp_ge_f32_e64 s[4:5], 0, v103
	v_add_u32_e32 v103, 1, v101
	s_nop 0
	v_cndmask_b32_e64 v102, v101, v102, s[4:5]
	v_fma_f32 v101, -v103, v101, v100
	v_cmp_lt_f32_e64 s[4:5], 0, v101
	s_nop 1
	v_cndmask_b32_e64 v101, v102, v103, s[4:5]
	v_mul_f32_e32 v102, 0x37800000, v101
	v_cndmask_b32_e32 v101, v101, v102, vcc
	v_cmp_class_f32_e32 vcc, v100, v226
	s_nop 1
	v_cndmask_b32_e32 v100, v101, v100, vcc
	v_div_scale_f32 v101, s[0:1], v100, v100, 1.0
	v_rcp_f32_e32 v102, v101
	s_nop 0
	v_fma_f32 v103, -v101, v102, 1.0
	v_fmac_f32_e32 v102, v103, v102
	v_div_scale_f32 v103, vcc, 1.0, v100, 1.0
	v_mul_f32_e32 v104, v103, v102
	v_fma_f32 v105, -v101, v104, v103
	v_fmac_f32_e32 v104, v105, v102
	v_fma_f32 v101, -v101, v104, v103
	v_div_fmas_f32 v101, v101, v102, v104
	v_div_fixup_f32 v100, v101, v100, 1.0
	ds_write_b32 v3, v100 offset:6144
.LBB0_367:
	s_or_b64 exec, exec, s[6:7]
	s_cmp_eq_u32 s71, 0
	s_waitcnt lgkmcnt(0)
	s_barrier
	s_load_dwordx2 s[12:13], s[2:3], 0x18
	s_movk_i32 s0, 44
	s_lshl_b32 s20, s0, 6
	v_readlane_b32 s1, v252, 9
	v_mbcnt_lo_u32_b32 v0, -1, 0
	v_mbcnt_hi_u32_b32 v0, -1, v0
	s_cmp_lt_i32 s43, s20
	s_cselect_b64 s[2:3], -1, 0
	v_add_u32_e32 v8, s1, v0
	s_cmp_ge_i32 s43, s20
	v_readfirstlane_b32 s1, v8
	s_cbranch_scc1 .LBB0_369
	s_lshl_b32 s4, s0, 3
	s_abs_i32 s7, s4
	v_cvt_f32_u32_e32 v0, s7
	s_ashr_i32 s5, s43, 31
	s_lshr_b32 s5, s5, 29
	s_add_i32 s5, s43, s5
	v_rcp_iflag_f32_e32 v0, v0
	s_ashr_i32 s6, s5, 3
	s_and_b32 s5, s5, -8
	s_sub_i32 s5, s43, s5
	v_mul_f32_e32 v0, 0x4f7ffffe, v0
	v_cvt_u32_f32_e32 v0, v0
	s_lshr_b32 s14, s5, 31
	s_or_b32 s14, s4, s14
	s_sub_i32 s15, 0, s7
	v_readfirstlane_b32 s16, v0
	s_mul_i32 s5, s5, s14
	s_mul_i32 s15, s15, s16
	s_add_i32 s5, s5, s6
	s_mul_hi_u32 s15, s16, s15
	s_abs_i32 s14, s5
	s_add_i32 s16, s16, s15
	s_mul_hi_u32 s15, s14, s16
	s_mul_i32 s16, s15, s7
	s_xor_b32 s6, s5, s4
	s_sub_i32 s14, s14, s16
	s_ashr_i32 s6, s6, 31
	s_add_i32 s16, s15, 1
	s_sub_i32 s17, s14, s7
	s_cmp_ge_u32 s14, s7
	s_cselect_b32 s15, s16, s15
	s_cselect_b32 s14, s17, s14
	s_add_i32 s16, s15, 1
	s_cmp_ge_u32 s14, s7
	s_cselect_b32 s7, s16, s15
	s_xor_b32 s7, s7, s6
	s_sub_i32 s6, s7, s6
	s_lshl_b32 s7, s6, 3
	s_sub_i32 s14, 64, s7
	s_min_u32 s14, s14, 8
	s_mul_i32 s6, s6, s4
	s_sub_i32 s6, s5, s6
	v_cvt_f32_ubyte0_e32 v1, s14
	v_cvt_f32_i32_e32 v0, s6
	v_rcp_iflag_f32_e32 v2, v1
	s_ashr_i32 s4, s6, 30
	s_or_b32 s15, s4, 1
	v_mul_f32_e32 v2, v0, v2
	v_trunc_f32_e32 v2, v2
	v_fma_f32 v0, -v2, v1, v0
	v_cvt_i32_f32_e32 v2, v2
	v_cmp_ge_f32_e64 s[4:5], |v0|, v1
	s_and_b64 s[4:5], s[4:5], exec
	s_cselect_b32 s4, s15, 0
	v_readfirstlane_b32 s5, v2
	s_add_i32 s5, s5, s4
	s_sext_i32_i16 s4, s5
	s_mul_i32 s5, s5, s14
	s_sub_i32 s5, s6, s5
	s_sext_i32_i16 s5, s5
	s_add_i32 s30, s7, s5

; #define LAS __attribute__((address_space(3)))
;     DI void init(const bf16* A_, int lda, const bf16* B_, int ldb, int nM, int nN, int K, int G_, int c_) { T.init(nM, nN); G = G_; c = c_; nt = K / BK; A = (const char*)A_; B = (const char*)B_; ta = (size_t)BM * lda * 2; tb = (size_t)BM * ldb * 2; }
;     DI void init(const bf16* A_, int lda, const bf16* B_, int ldb, int nM, int nN, int G_, int c_) { T.init(nM, nN); G = G_; c = c_; A = (const char*)A_; B = (const char*)B_; ta = (size_t)BM * lda * 2; tb = (size_t)BM * ldb * 2; }
; #define SEAM(k) do { if (IN((k) + 1) && IN(k)) xcd_barrier(bar); } while (0)
; #define FRAME() const CAS Args* ap; const Frame F = make_frame(lds, ap, wv); const CAS Args& A = *ap; (void)A
; __global__ void __launch_bounds__(512, 2) trunk_fwd(Args args_unused) {
;     ...
;         if (PHEN(1) && IN(s0 + 1)) { FRAME();
;             const int nN = (l == 0) ? 44 : 45;
;             const LAS float* rs = rstd_table(F);
;             SchedPlain S; S.init((const bf16*)F.out, XP, (const bf16*)lw(F, l, LW_WIN), D, M / BM, nN, D, F.G, F.bid);
;             EpiInproj E{(bf16*)(F.ws + WS_R2), A.in[3] + (size_t)l * 6144, (bf16*)(F.ws + WS_ZS5), rs};
;             gemm_phase<EpiInproj, SchedPlain>(F.lds, F.wave, XP, D, S, E);
;             SEAM(s0 + 1);
.LBB0_489:
	s_cmp_eq_u32 s71, 0
	s_cbranch_scc1 .Lvres_done
	s_load_dwordx4 s[4:7], s[88:89], 0x130
	v_mbcnt_lo_u32_b32 v181, -1, 0
	v_mbcnt_hi_u32_b32 v181, -1, v181
	v_readlane_b32 s0, v252, 0
	v_and_b32_e32 v182, 15, v181
	v_lshrrev_b32_e32 v183, 4, v181
	s_and_b32 s1, s90, 3
	s_lshl_b32 s0, s0, 6
	s_lshl_b32 s1, s1, 4
	s_add_i32 s0, s0, s1
	v_add_u32_e32 v184, s0, v182
	v_lshlrev_b32_e32 v178, 7, v184
	v_lshlrev_b32_e32 v176, 12, v184
	v_lshl_add_u32 v176, v183, 4, v176
	v_lshlrev_b32_e32 v174, 12, v182
	v_lshl_add_u32 v174, v183, 4, v174
	v_mul_u32_u24_e32 v170, 0x5a00, v184
	v_lshl_add_u32 v170, v183, 3, v170
	s_lshr_b32 s1, s90, 2
	s_lshl_b32 s2, s1, 1
	s_add_i32 s3, s1, 1
	s_mul_i32 s17, s71, 0x7eca000
	s_waitcnt lgkmcnt(0)
	s_add_u32 s16, s6, 0x49c28000
	s_addc_u32 s101, s7, 0
	s_mov_b32 s100, s16
	global_load_dwordx4 v[196:199], v178, s[100:101] offset:32
	global_load_dwordx4 v[200:203], v178, s[100:101] offset:48
	global_load_dwordx4 v[204:207], v178, s[100:101]
	global_load_dwordx4 v[208:211], v178, s[100:101] offset:16
	global_load_dwordx4 v[212:215], v178, s[100:101] offset:96
	global_load_dwordx4 v[216:219], v178, s[100:101] offset:112
	global_load_dwordx4 v[220:223], v178, s[100:101] offset:64
	global_load_dwordx4 v[234:237], v178, s[100:101] offset:80
	s_add_u32 s16, s6, s17
	s_addc_u32 s17, s7, 0
	s_add_u32 s16, s16, 0x2d00000
	s_addc_u32 s17, s17, 0
	s_lshl_b32 s0, s2, 16
	s_lshl_b32 s1, s3, 16
	s_add_u32 s98, s16, s1
	s_addc_u32 s99, s17, 0
	s_add_u32 s0, s16, s0
	s_addc_u32 s1, s17, 0
	s_lshl_b32 s2, s2, 5
	s_lshl_b32 s3, s3, 5
	s_add_u32 s16, s6, 0x23c2d800
	s_addc_u32 s17, s7, 0
	s_add_u32 s6, s16, s3
	s_addc_u32 s7, s17, 0
	s_add_u32 s16, s16, s2
	s_addc_u32 s17, s17, 0
	global_load_dwordx4 v[0:3], v176, s[4:5]
	global_load_dwordx4 v[4:7], v174, s[0:1]
	global_load_dwordx4 v[8:11], v174, s[98:99]
	global_load_dwordx4 v[12:15], v176, s[4:5] offset:64
	global_load_dwordx4 v[16:19], v174, s[0:1] offset:64
	global_load_dwordx4 v[20:23], v174, s[98:99] offset:64
	global_load_dwordx4 v[24:27], v176, s[4:5] offset:128
	global_load_dwordx4 v[28:31], v174, s[0:1] offset:128
	global_load_dwordx4 v[32:35], v174, s[98:99] offset:128
	global_load_dwordx4 v[36:39], v176, s[4:5] offset:192
	global_load_dwordx4 v[40:43], v174, s[0:1] offset:192
	global_load_dwordx4 v[44:47], v174, s[98:99] offset:192
	global_load_dwordx4 v[48:51], v176, s[4:5] offset:256
	global_load_dwordx4 v[52:55], v174, s[0:1] offset:256
	global_load_dwordx4 v[56:59], v174, s[98:99] offset:256
	global_load_dwordx4 v[60:63], v176, s[4:5] offset:320
	global_load_dwordx4 v[64:67], v174, s[0:1] offset:320
	global_load_dwordx4 v[68:71], v174, s[98:99] offset:320
	global_load_dwordx4 v[72:75], v176, s[4:5] offset:384
	global_load_dwordx4 v[76:79], v174, s[0:1] offset:384
	global_load_dwordx4 v[80:83], v174, s[98:99] offset:384
	global_load_dwordx4 v[84:87], v176, s[4:5] offset:448
	global_load_dwordx4 v[88:91], v174, s[0:1] offset:448
	global_load_dwordx4 v[92:95], v174, s[98:99] offset:448
	global_load_dwordx4 v[96:99], v176, s[4:5] offset:512
	global_load_dwordx4 v[100:103], v174, s[0:1] offset:512
	global_load_dwordx4 v[104:107], v174, s[98:99] offset:512
	global_load_dwordx4 v[108:111], v176, s[4:5] offset:576
	global_load_dwordx4 v[112:115], v174, s[0:1] offset:576
	global_load_dwordx4 v[116:119], v174, s[98:99] offset:576
	global_load_dwordx4 v[120:123], v176, s[4:5] offset:640
	global_load_dwordx4 v[124:127], v174, s[0:1] offset:640
	global_load_dwordx4 v[128:131], v174, s[98:99] offset:640
	global_load_dwordx4 v[132:135], v176, s[4:5] offset:704
	global_load_dwordx4 v[136:139], v174, s[0:1] offset:704
	global_load_dwordx4 v[140:143], v174, s[98:99] offset:704
	global_load_dwordx4 v[144:147], v176, s[4:5] offset:768
	global_load_dwordx4 v[148:151], v174, s[0:1] offset:768
	global_load_dwordx4 v[152:155], v174, s[98:99] offset:768
	s_waitcnt vmcnt(36)
	v_mfma_f32_16x16x32_bf16 v[160:163], v[4:7], v[0:3], 0
	v_mfma_f32_16x16x32_bf16 v[164:167], v[8:11], v[0:3], 0
	global_load_dwordx4 v[0:3], v176, s[4:5] offset:832
	global_load_dwordx4 v[4:7], v174, s[0:1] offset:832
	global_load_dwordx4 v[8:11], v174, s[98:99] offset:832
	s_waitcnt vmcnt(36)
	v_mfma_f32_16x16x32_bf16 v[160:163], v[16:19], v[12:15], v[160:163]
	v_mfma_f32_16x16x32_bf16 v[164:167], v[20:23], v[12:15], v[164:167]
	global_load_dwordx4 v[12:15], v176, s[4:5] offset:896
	global_load_dwordx4 v[16:19], v174, s[0:1] offset:896
	global_load_dwordx4 v[20:23], v174, s[98:99] offset:896
	s_waitcnt vmcnt(36)
	v_mfma_f32_16x16x32_bf16 v[160:163], v[28:31], v[24:27], v[160:163]
	v_mfma_f32_16x16x32_bf16 v[164:167], v[32:35], v[24:27], v[164:167]
	global_load_dwordx4 v[24:27], v176, s[4:5] offset:960
	global_load_dwordx4 v[28:31], v174, s[0:1] offset:960
	global_load_dwordx4 v[32:35], v174, s[98:99] offset:960
	s_waitcnt vmcnt(36)
	v_mfma_f32_16x16x32_bf16 v[160:163], v[40:43], v[36:39], v[160:163]
	v_mfma_f32_16x16x32_bf16 v[164:167], v[44:47], v[36:39], v[164:167]
	global_load_dwordx4 v[36:39], v176, s[4:5] offset:1024
	global_load_dwordx4 v[40:43], v174, s[0:1] offset:1024
	global_load_dwordx4 v[44:47], v174, s[98:99] offset:1024
	s_waitcnt vmcnt(36)
	v_mfma_f32_16x16x32_bf16 v[160:163], v[52:55], v[48:51], v[160:163]
	v_mfma_f32_16x16x32_bf16 v[164:167], v[56:59], v[48:51], v[164:167]
	global_load_dwordx4 v[48:51], v176, s[4:5] offset:1088
	global_load_dwordx4 v[52:55], v174, s[0:1] offset:1088
	global_load_dwordx4 v[56:59], v174, s[98:99] offset:1088
	s_waitcnt vmcnt(36)
; #define LAS __attribute__((address_space(3)))
;     DI void init(const bf16* A_, int lda, const bf16* B_, int ldb, int nM, int nN, int K, int G_, int c_) { T.init(nM, nN); G = G_; c = c_; nt = K / BK; A = (const char*)A_; B = (const char*)B_; ta = (size_t)BM * lda * 2; tb = (size_t)BM * ldb * 2; }
;     DI void init(const bf16* A_, int lda, const bf16* B_, int ldb, int nM, int nN, int G_, int c_) { T.init(nM, nN); G = G_; c = c_; A = (const char*)A_; B = (const char*)B_; ta = (size_t)BM * lda * 2; tb = (size_t)BM * ldb * 2; }
; #define SEAM(k) do { if (IN((k) + 1) && IN(k)) xcd_barrier(bar); } while (0)
; #define FRAME() const CAS Args* ap; const Frame F = make_frame(lds, ap, wv); const CAS Args& A = *ap; (void)A
; __global__ void __launch_bounds__(512, 2) trunk_fwd(Args args_unused) {
;     ...
;         if (PHEN(1) && IN(s0 + 1)) { FRAME();
;             const int nN = (l == 0) ? 44 : 45;
;             const LAS float* rs = rstd_table(F);
;             SchedPlain S; S.init((const bf16*)F.out, XP, (const bf16*)lw(F, l, LW_WIN), D, M / BM, nN, D, F.G, F.bid);
;             EpiInproj E{(bf16*)(F.ws + WS_R2), A.in[3] + (size_t)l * 6144, (bf16*)(F.ws + WS_ZS5), rs};
;             gemm_phase<EpiInproj, SchedPlain>(F.lds, F.wave, XP, D, S, E);
;             SEAM(s0 + 1);
	v_mfma_f32_16x16x32_bf16 v[160:163], v[64:67], v[60:63], v[160:163]
	v_mfma_f32_16x16x32_bf16 v[164:167], v[68:71], v[60:63], v[164:167]
	global_load_dwordx4 v[60:63], v176, s[4:5] offset:1152
	global_load_dwordx4 v[64:67], v174, s[0:1] offset:1152
	global_load_dwordx4 v[68:71], v174, s[98:99] offset:1152
	s_waitcnt vmcnt(36)
	v_mfma_f32_16x16x32_bf16 v[160:163], v[76:79], v[72:75], v[160:163]
	v_mfma_f32_16x16x32_bf16 v[164:167], v[80:83], v[72:75], v[164:167]
	global_load_dwordx4 v[72:75], v176, s[4:5] offset:1216
	global_load_dwordx4 v[76:79], v174, s[0:1] offset:1216
	global_load_dwordx4 v[80:83], v174, s[98:99] offset:1216
	s_waitcnt vmcnt(36)
	v_mfma_f32_16x16x32_bf16 v[160:163], v[88:91], v[84:87], v[160:163]
	v_mfma_f32_16x16x32_bf16 v[164:167], v[92:95], v[84:87], v[164:167]
	global_load_dwordx4 v[84:87], v176, s[4:5] offset:1280
	global_load_dwordx4 v[88:91], v174, s[0:1] offset:1280
	global_load_dwordx4 v[92:95], v174, s[98:99] offset:1280
	s_waitcnt vmcnt(36)
	v_mfma_f32_16x16x32_bf16 v[160:163], v[100:103], v[96:99], v[160:163]
	v_mfma_f32_16x16x32_bf16 v[164:167], v[104:107], v[96:99], v[164:167]
	global_load_dwordx4 v[96:99], v176, s[4:5] offset:1344
	global_load_dwordx4 v[100:103], v174, s[0:1] offset:1344
	global_load_dwordx4 v[104:107], v174, s[98:99] offset:1344
	s_waitcnt vmcnt(36)
	v_mfma_f32_16x16x32_bf16 v[160:163], v[112:115], v[108:111], v[160:163]
	v_mfma_f32_16x16x32_bf16 v[164:167], v[116:119], v[108:111], v[164:167]
	global_load_dwordx4 v[108:111], v176, s[4:5] offset:1408
	global_load_dwordx4 v[112:115], v174, s[0:1] offset:1408
	global_load_dwordx4 v[116:119], v174, s[98:99] offset:1408
	s_waitcnt vmcnt(36)
	v_mfma_f32_16x16x32_bf16 v[160:163], v[124:127], v[120:123], v[160:163]
	v_mfma_f32_16x16x32_bf16 v[164:167], v[128:131], v[120:123], v[164:167]
	global_load_dwordx4 v[120:123], v176, s[4:5] offset:1472
	global_load_dwordx4 v[124:127], v174, s[0:1] offset:1472
	global_load_dwordx4 v[128:131], v174, s[98:99] offset:1472
	s_waitcnt vmcnt(36)
	v_mfma_f32_16x16x32_bf16 v[160:163], v[136:139], v[132:135], v[160:163]
	v_mfma_f32_16x16x32_bf16 v[164:167], v[140:143], v[132:135], v[164:167]
	global_load_dwordx4 v[132:135], v176, s[4:5] offset:1536
	global_load_dwordx4 v[136:139], v174, s[0:1] offset:1536
	global_load_dwordx4 v[140:143], v174, s[98:99] offset:1536
	s_waitcnt vmcnt(36)
	v_mfma_f32_16x16x32_bf16 v[160:163], v[148:151], v[144:147], v[160:163]
	v_mfma_f32_16x16x32_bf16 v[164:167], v[152:155], v[144:147], v[164:167]
	global_load_dwordx4 v[144:147], v176, s[4:5] offset:1600
	global_load_dwordx4 v[148:151], v174, s[0:1] offset:1600
	global_load_dwordx4 v[152:155], v174, s[98:99] offset:1600
	s_waitcnt vmcnt(36)
	v_mfma_f32_16x16x32_bf16 v[160:163], v[4:7], v[0:3], v[160:163]
	v_mfma_f32_16x16x32_bf16 v[164:167], v[8:11], v[0:3], v[164:167]
	global_load_dwordx4 v[0:3], v176, s[4:5] offset:1664
	global_load_dwordx4 v[4:7], v174, s[0:1] offset:1664
	global_load_dwordx4 v[8:11], v174, s[98:99] offset:1664
	s_waitcnt vmcnt(36)
	v_mfma_f32_16x16x32_bf16 v[160:163], v[16:19], v[12:15], v[160:163]
	v_mfma_f32_16x16x32_bf16 v[164:167], v[20:23], v[12:15], v[164:167]
	global_load_dwordx4 v[12:15], v176, s[4:5] offset:1728
	global_load_dwordx4 v[16:19], v174, s[0:1] offset:1728
	global_load_dwordx4 v[20:23], v174, s[98:99] offset:1728
	s_waitcnt vmcnt(36)
	v_mfma_f32_16x16x32_bf16 v[160:163], v[28:31], v[24:27], v[160:163]
	v_mfma_f32_16x16x32_bf16 v[164:167], v[32:35], v[24:27], v[164:167]
	global_load_dwordx4 v[24:27], v176, s[4:5] offset:1792
	global_load_dwordx4 v[28:31], v174, s[0:1] offset:1792
	global_load_dwordx4 v[32:35], v174, s[98:99] offset:1792
	s_waitcnt vmcnt(36)
	v_mfma_f32_16x16x32_bf16 v[160:163], v[40:43], v[36:39], v[160:163]
	v_mfma_f32_16x16x32_bf16 v[164:167], v[44:47], v[36:39], v[164:167]
	global_load_dwordx4 v[36:39], v176, s[4:5] offset:1856
	global_load_dwordx4 v[40:43], v174, s[0:1] offset:1856
	global_load_dwordx4 v[44:47], v174, s[98:99] offset:1856
	s_waitcnt vmcnt(36)
	v_mfma_f32_16x16x32_bf16 v[160:163], v[52:55], v[48:51], v[160:163]
	v_mfma_f32_16x16x32_bf16 v[164:167], v[56:59], v[48:51], v[164:167]
	global_load_dwordx4 v[48:51], v176, s[4:5] offset:1920
	global_load_dwordx4 v[52:55], v174, s[0:1] offset:1920
	global_load_dwordx4 v[56:59], v174, s[98:99] offset:1920
	s_waitcnt vmcnt(36)
	v_mfma_f32_16x16x32_bf16 v[160:163], v[64:67], v[60:63], v[160:163]
	v_mfma_f32_16x16x32_bf16 v[164:167], v[68:71], v[60:63], v[164:167]
	global_load_dwordx4 v[60:63], v176, s[4:5] offset:1984
	global_load_dwordx4 v[64:67], v174, s[0:1] offset:1984
	global_load_dwordx4 v[68:71], v174, s[98:99] offset:1984
	s_waitcnt vmcnt(36)
	v_mfma_f32_16x16x32_bf16 v[160:163], v[76:79], v[72:75], v[160:163]
	v_mfma_f32_16x16x32_bf16 v[164:167], v[80:83], v[72:75], v[164:167]
	global_load_dwordx4 v[72:75], v176, s[4:5] offset:2048
	global_load_dwordx4 v[76:79], v174, s[0:1] offset:2048
	global_load_dwordx4 v[80:83], v174, s[98:99] offset:2048
	s_waitcnt vmcnt(36)
	v_mfma_f32_16x16x32_bf16 v[160:163], v[88:91], v[84:87], v[160:163]
	v_mfma_f32_16x16x32_bf16 v[164:167], v[92:95], v[84:87], v[164:167]
	global_load_dwordx4 v[84:87], v176, s[4:5] offset:2112
	global_load_dwordx4 v[88:91], v174, s[0:1] offset:2112
	global_load_dwordx4 v[92:95], v174, s[98:99] offset:2112
	s_waitcnt vmcnt(36)
	v_mfma_f32_16x16x32_bf16 v[160:163], v[100:103], v[96:99], v[160:163]
	v_mfma_f32_16x16x32_bf16 v[164:167], v[104:107], v[96:99], v[164:167]
	global_load_dwordx4 v[96:99], v176, s[4:5] offset:2176
	global_load_dwordx4 v[100:103], v174, s[0:1] offset:2176
	global_load_dwordx4 v[104:107], v174, s[98:99] offset:2176
	s_waitcnt vmcnt(36)
; #define LAS __attribute__((address_space(3)))
;     DI void init(const bf16* A_, int lda, const bf16* B_, int ldb, int nM, int nN, int K, int G_, int c_) { T.init(nM, nN); G = G_; c = c_; nt = K / BK; A = (const char*)A_; B = (const char*)B_; ta = (size_t)BM * lda * 2; tb = (size_t)BM * ldb * 2; }
;     DI void init(const bf16* A_, int lda, const bf16* B_, int ldb, int nM, int nN, int G_, int c_) { T.init(nM, nN); G = G_; c = c_; A = (const char*)A_; B = (const char*)B_; ta = (size_t)BM * lda * 2; tb = (size_t)BM * ldb * 2; }
; #define SEAM(k) do { if (IN((k) + 1) && IN(k)) xcd_barrier(bar); } while (0)
; #define FRAME() const CAS Args* ap; const Frame F = make_frame(lds, ap, wv); const CAS Args& A = *ap; (void)A
; __global__ void __launch_bounds__(512, 2) trunk_fwd(Args args_unused) {
;     ...
;         if (PHEN(1) && IN(s0 + 1)) { FRAME();
;             const int nN = (l == 0) ? 44 : 45;
;             const LAS float* rs = rstd_table(F);
;             SchedPlain S; S.init((const bf16*)F.out, XP, (const bf16*)lw(F, l, LW_WIN), D, M / BM, nN, D, F.G, F.bid);
;             EpiInproj E{(bf16*)(F.ws + WS_R2), A.in[3] + (size_t)l * 6144, (bf16*)(F.ws + WS_ZS5), rs};
;             gemm_phase<EpiInproj, SchedPlain>(F.lds, F.wave, XP, D, S, E);
;             SEAM(s0 + 1);
	v_mfma_f32_16x16x32_bf16 v[160:163], v[112:115], v[108:111], v[160:163]
	v_mfma_f32_16x16x32_bf16 v[164:167], v[116:119], v[108:111], v[164:167]
	global_load_dwordx4 v[108:111], v176, s[4:5] offset:2240
	global_load_dwordx4 v[112:115], v174, s[0:1] offset:2240
	global_load_dwordx4 v[116:119], v174, s[98:99] offset:2240
	s_waitcnt vmcnt(36)
	v_mfma_f32_16x16x32_bf16 v[160:163], v[124:127], v[120:123], v[160:163]
	v_mfma_f32_16x16x32_bf16 v[164:167], v[128:131], v[120:123], v[164:167]
	global_load_dwordx4 v[120:123], v176, s[4:5] offset:2304
	global_load_dwordx4 v[124:127], v174, s[0:1] offset:2304
	global_load_dwordx4 v[128:131], v174, s[98:99] offset:2304
	s_waitcnt vmcnt(36)
	v_mfma_f32_16x16x32_bf16 v[160:163], v[136:139], v[132:135], v[160:163]
	v_mfma_f32_16x16x32_bf16 v[164:167], v[140:143], v[132:135], v[164:167]
	global_load_dwordx4 v[132:135], v176, s[4:5] offset:2368
	global_load_dwordx4 v[136:139], v174, s[0:1] offset:2368
	global_load_dwordx4 v[140:143], v174, s[98:99] offset:2368
	s_waitcnt vmcnt(36)
	v_mfma_f32_16x16x32_bf16 v[160:163], v[148:151], v[144:147], v[160:163]
	v_mfma_f32_16x16x32_bf16 v[164:167], v[152:155], v[144:147], v[164:167]
	global_load_dwordx4 v[144:147], v176, s[4:5] offset:2432
	global_load_dwordx4 v[148:151], v174, s[0:1] offset:2432
	global_load_dwordx4 v[152:155], v174, s[98:99] offset:2432
	s_waitcnt vmcnt(36)
	v_mfma_f32_16x16x32_bf16 v[160:163], v[4:7], v[0:3], v[160:163]
	v_mfma_f32_16x16x32_bf16 v[164:167], v[8:11], v[0:3], v[164:167]
	global_load_dwordx4 v[0:3], v176, s[4:5] offset:2496
	global_load_dwordx4 v[4:7], v174, s[0:1] offset:2496
	global_load_dwordx4 v[8:11], v174, s[98:99] offset:2496
	s_waitcnt vmcnt(36)
	v_mfma_f32_16x16x32_bf16 v[160:163], v[16:19], v[12:15], v[160:163]
	v_mfma_f32_16x16x32_bf16 v[164:167], v[20:23], v[12:15], v[164:167]
	global_load_dwordx4 v[12:15], v176, s[4:5] offset:2560
	global_load_dwordx4 v[16:19], v174, s[0:1] offset:2560
	global_load_dwordx4 v[20:23], v174, s[98:99] offset:2560
	s_waitcnt vmcnt(36)
	v_mfma_f32_16x16x32_bf16 v[160:163], v[28:31], v[24:27], v[160:163]
	v_mfma_f32_16x16x32_bf16 v[164:167], v[32:35], v[24:27], v[164:167]
	global_load_dwordx4 v[24:27], v176, s[4:5] offset:2624
	global_load_dwordx4 v[28:31], v174, s[0:1] offset:2624
	global_load_dwordx4 v[32:35], v174, s[98:99] offset:2624
	s_waitcnt vmcnt(36)
	v_mfma_f32_16x16x32_bf16 v[160:163], v[40:43], v[36:39], v[160:163]
	v_mfma_f32_16x16x32_bf16 v[164:167], v[44:47], v[36:39], v[164:167]
	global_load_dwordx4 v[36:39], v176, s[4:5] offset:2688
	global_load_dwordx4 v[40:43], v174, s[0:1] offset:2688
	global_load_dwordx4 v[44:47], v174, s[98:99] offset:2688
	s_waitcnt vmcnt(36)
	v_mfma_f32_16x16x32_bf16 v[160:163], v[52:55], v[48:51], v[160:163]
	v_mfma_f32_16x16x32_bf16 v[164:167], v[56:59], v[48:51], v[164:167]
	global_load_dwordx4 v[48:51], v176, s[4:5] offset:2752
	global_load_dwordx4 v[52:55], v174, s[0:1] offset:2752
	global_load_dwordx4 v[56:59], v174, s[98:99] offset:2752
	s_waitcnt vmcnt(36)
	v_mfma_f32_16x16x32_bf16 v[160:163], v[64:67], v[60:63], v[160:163]
	v_mfma_f32_16x16x32_bf16 v[164:167], v[68:71], v[60:63], v[164:167]
	global_load_dwordx4 v[60:63], v176, s[4:5] offset:2816
	global_load_dwordx4 v[64:67], v174, s[0:1] offset:2816
	global_load_dwordx4 v[68:71], v174, s[98:99] offset:2816
	s_waitcnt vmcnt(36)
	v_mfma_f32_16x16x32_bf16 v[160:163], v[76:79], v[72:75], v[160:163]
	v_mfma_f32_16x16x32_bf16 v[164:167], v[80:83], v[72:75], v[164:167]
	global_load_dwordx4 v[72:75], v176, s[4:5] offset:2880
	global_load_dwordx4 v[76:79], v174, s[0:1] offset:2880
	global_load_dwordx4 v[80:83], v174, s[98:99] offset:2880
	s_waitcnt vmcnt(36)
	v_mfma_f32_16x16x32_bf16 v[160:163], v[88:91], v[84:87], v[160:163]
	v_mfma_f32_16x16x32_bf16 v[164:167], v[92:95], v[84:87], v[164:167]
	global_load_dwordx4 v[84:87], v176, s[4:5] offset:2944
	global_load_dwordx4 v[88:91], v174, s[0:1] offset:2944
	global_load_dwordx4 v[92:95], v174, s[98:99] offset:2944
	s_waitcnt vmcnt(36)
	v_mfma_f32_16x16x32_bf16 v[160:163], v[100:103], v[96:99], v[160:163]
	v_mfma_f32_16x16x32_bf16 v[164:167], v[104:107], v[96:99], v[164:167]
	global_load_dwordx4 v[96:99], v176, s[4:5] offset:3008
	global_load_dwordx4 v[100:103], v174, s[0:1] offset:3008
	global_load_dwordx4 v[104:107], v174, s[98:99] offset:3008
	s_waitcnt vmcnt(36)
	v_mfma_f32_16x16x32_bf16 v[160:163], v[112:115], v[108:111], v[160:163]
	v_mfma_f32_16x16x32_bf16 v[164:167], v[116:119], v[108:111], v[164:167]
	global_load_dwordx4 v[108:111], v176, s[4:5] offset:3072
	global_load_dwordx4 v[112:115], v174, s[0:1] offset:3072
	global_load_dwordx4 v[116:119], v174, s[98:99] offset:3072
	s_waitcnt vmcnt(36)
	v_mfma_f32_16x16x32_bf16 v[160:163], v[124:127], v[120:123], v[160:163]
	v_mfma_f32_16x16x32_bf16 v[164:167], v[128:131], v[120:123], v[164:167]
	global_load_dwordx4 v[120:123], v176, s[4:5] offset:3136
	global_load_dwordx4 v[124:127], v174, s[0:1] offset:3136
	global_load_dwordx4 v[128:131], v174, s[98:99] offset:3136
	s_waitcnt vmcnt(36)
	v_mfma_f32_16x16x32_bf16 v[160:163], v[136:139], v[132:135], v[160:163]
	v_mfma_f32_16x16x32_bf16 v[164:167], v[140:143], v[132:135], v[164:167]
	global_load_dwordx4 v[132:135], v176, s[4:5] offset:3200
	global_load_dwordx4 v[136:139], v174, s[0:1] offset:3200
	global_load_dwordx4 v[140:143], v174, s[98:99] offset:3200
	s_waitcnt vmcnt(36)
	v_mfma_f32_16x16x32_bf16 v[160:163], v[148:151], v[144:147], v[160:163]
	v_mfma_f32_16x16x32_bf16 v[164:167], v[152:155], v[144:147], v[164:167]
	global_load_dwordx4 v[144:147], v176, s[4:5] offset:3264
	global_load_dwordx4 v[148:151], v174, s[0:1] offset:3264
	global_load_dwordx4 v[152:155], v174, s[98:99] offset:3264
	s_waitcnt vmcnt(36)
; #define LAS __attribute__((address_space(3)))
;     DI void init(const bf16* A_, int lda, const bf16* B_, int ldb, int nM, int nN, int K, int G_, int c_) { T.init(nM, nN); G = G_; c = c_; nt = K / BK; A = (const char*)A_; B = (const char*)B_; ta = (size_t)BM * lda * 2; tb = (size_t)BM * ldb * 2; }
;     DI void init(const bf16* A_, int lda, const bf16* B_, int ldb, int nM, int nN, int G_, int c_) { T.init(nM, nN); G = G_; c = c_; A = (const char*)A_; B = (const char*)B_; ta = (size_t)BM * lda * 2; tb = (size_t)BM * ldb * 2; }
; #define SEAM(k) do { if (IN((k) + 1) && IN(k)) xcd_barrier(bar); } while (0)
; #define FRAME() const CAS Args* ap; const Frame F = make_frame(lds, ap, wv); const CAS Args& A = *ap; (void)A
; __global__ void __launch_bounds__(512, 2) trunk_fwd(Args args_unused) {
;     ...
;         if (PHEN(1) && IN(s0 + 1)) { FRAME();
;             const int nN = (l == 0) ? 44 : 45;
;             const LAS float* rs = rstd_table(F);
;             SchedPlain S; S.init((const bf16*)F.out, XP, (const bf16*)lw(F, l, LW_WIN), D, M / BM, nN, D, F.G, F.bid);
;             EpiInproj E{(bf16*)(F.ws + WS_R2), A.in[3] + (size_t)l * 6144, (bf16*)(F.ws + WS_ZS5), rs};
;             gemm_phase<EpiInproj, SchedPlain>(F.lds, F.wave, XP, D, S, E);
;             SEAM(s0 + 1);
	v_mfma_f32_16x16x32_bf16 v[160:163], v[4:7], v[0:3], v[160:163]
	v_mfma_f32_16x16x32_bf16 v[164:167], v[8:11], v[0:3], v[164:167]
	global_load_dwordx4 v[0:3], v176, s[4:5] offset:3328
	global_load_dwordx4 v[4:7], v174, s[0:1] offset:3328
	global_load_dwordx4 v[8:11], v174, s[98:99] offset:3328
	s_waitcnt vmcnt(36)
	v_mfma_f32_16x16x32_bf16 v[160:163], v[16:19], v[12:15], v[160:163]
	v_mfma_f32_16x16x32_bf16 v[164:167], v[20:23], v[12:15], v[164:167]
	global_load_dwordx4 v[12:15], v176, s[4:5] offset:3392
	global_load_dwordx4 v[16:19], v174, s[0:1] offset:3392
	global_load_dwordx4 v[20:23], v174, s[98:99] offset:3392
	s_waitcnt vmcnt(36)
	v_mfma_f32_16x16x32_bf16 v[160:163], v[28:31], v[24:27], v[160:163]
	v_mfma_f32_16x16x32_bf16 v[164:167], v[32:35], v[24:27], v[164:167]
	global_load_dwordx4 v[24:27], v176, s[4:5] offset:3456
	global_load_dwordx4 v[28:31], v174, s[0:1] offset:3456
	global_load_dwordx4 v[32:35], v174, s[98:99] offset:3456
	s_waitcnt vmcnt(36)
	v_mfma_f32_16x16x32_bf16 v[160:163], v[40:43], v[36:39], v[160:163]
	v_mfma_f32_16x16x32_bf16 v[164:167], v[44:47], v[36:39], v[164:167]
	global_load_dwordx4 v[36:39], v176, s[4:5] offset:3520
	global_load_dwordx4 v[40:43], v174, s[0:1] offset:3520
	global_load_dwordx4 v[44:47], v174, s[98:99] offset:3520
	s_waitcnt vmcnt(36)
	v_mfma_f32_16x16x32_bf16 v[160:163], v[52:55], v[48:51], v[160:163]
	v_mfma_f32_16x16x32_bf16 v[164:167], v[56:59], v[48:51], v[164:167]
	global_load_dwordx4 v[48:51], v176, s[4:5] offset:3584
	global_load_dwordx4 v[52:55], v174, s[0:1] offset:3584
	global_load_dwordx4 v[56:59], v174, s[98:99] offset:3584
	s_waitcnt vmcnt(36)
	v_mfma_f32_16x16x32_bf16 v[160:163], v[64:67], v[60:63], v[160:163]
	v_mfma_f32_16x16x32_bf16 v[164:167], v[68:71], v[60:63], v[164:167]
	global_load_dwordx4 v[60:63], v176, s[4:5] offset:3648
	global_load_dwordx4 v[64:67], v174, s[0:1] offset:3648
	global_load_dwordx4 v[68:71], v174, s[98:99] offset:3648
	s_waitcnt vmcnt(36)
	v_mfma_f32_16x16x32_bf16 v[160:163], v[76:79], v[72:75], v[160:163]
	v_mfma_f32_16x16x32_bf16 v[164:167], v[80:83], v[72:75], v[164:167]
	global_load_dwordx4 v[72:75], v176, s[4:5] offset:3712
	global_load_dwordx4 v[76:79], v174, s[0:1] offset:3712
	global_load_dwordx4 v[80:83], v174, s[98:99] offset:3712
	s_waitcnt vmcnt(36)
	v_mfma_f32_16x16x32_bf16 v[160:163], v[88:91], v[84:87], v[160:163]
	v_mfma_f32_16x16x32_bf16 v[164:167], v[92:95], v[84:87], v[164:167]
	global_load_dwordx4 v[84:87], v176, s[4:5] offset:3776
	global_load_dwordx4 v[88:91], v174, s[0:1] offset:3776
	global_load_dwordx4 v[92:95], v174, s[98:99] offset:3776
	s_waitcnt vmcnt(36)
	v_mfma_f32_16x16x32_bf16 v[160:163], v[100:103], v[96:99], v[160:163]
	v_mfma_f32_16x16x32_bf16 v[164:167], v[104:107], v[96:99], v[164:167]
	global_load_dwordx4 v[96:99], v176, s[4:5] offset:3840
	global_load_dwordx4 v[100:103], v174, s[0:1] offset:3840
	global_load_dwordx4 v[104:107], v174, s[98:99] offset:3840
	s_waitcnt vmcnt(36)
	v_mfma_f32_16x16x32_bf16 v[160:163], v[112:115], v[108:111], v[160:163]
	v_mfma_f32_16x16x32_bf16 v[164:167], v[116:119], v[108:111], v[164:167]
	global_load_dwordx4 v[108:111], v176, s[4:5] offset:3904
	global_load_dwordx4 v[112:115], v174, s[0:1] offset:3904
	global_load_dwordx4 v[116:119], v174, s[98:99] offset:3904
	s_waitcnt vmcnt(36)
	v_mfma_f32_16x16x32_bf16 v[160:163], v[124:127], v[120:123], v[160:163]
	v_mfma_f32_16x16x32_bf16 v[164:167], v[128:131], v[120:123], v[164:167]
	global_load_dwordx4 v[120:123], v176, s[4:5] offset:3968
	global_load_dwordx4 v[124:127], v174, s[0:1] offset:3968
	global_load_dwordx4 v[128:131], v174, s[98:99] offset:3968
	s_waitcnt vmcnt(36)
	v_mfma_f32_16x16x32_bf16 v[160:163], v[136:139], v[132:135], v[160:163]
	v_mfma_f32_16x16x32_bf16 v[164:167], v[140:143], v[132:135], v[164:167]
	global_load_dwordx4 v[132:135], v176, s[4:5] offset:4032
	global_load_dwordx4 v[136:139], v174, s[0:1] offset:4032
	global_load_dwordx4 v[140:143], v174, s[98:99] offset:4032
	s_waitcnt vmcnt(36)
	v_mfma_f32_16x16x32_bf16 v[160:163], v[148:151], v[144:147], v[160:163]
	v_mfma_f32_16x16x32_bf16 v[164:167], v[152:155], v[144:147], v[164:167]
	s_waitcnt vmcnt(33)
	v_mfma_f32_16x16x32_bf16 v[160:163], v[4:7], v[0:3], v[160:163]
	v_mfma_f32_16x16x32_bf16 v[164:167], v[8:11], v[0:3], v[164:167]
	s_waitcnt vmcnt(30)
; #define GAS __attribute__((address_space(1)))
; DI unsigned pk2(float lo, float hi) { f32x2 v = {lo, hi}; bf16x2_t r = __builtin_convertvector(v, bf16x2_t); return __builtin_bit_cast(unsigned, r); }
; DI float sigmoidf_(float x) { return __builtin_amdgcn_rcpf(1.f + __expf(-x)); }
;     DI bool operator()(AccT& acc, const Unit& u, int wr, int wc, int fr, int fq) const {
;     ...
;                     f32x4 v0 = acc[ai][bj][m][0] * rsv[ai][m], v1 = acc[ai][bj][m][1] * rsv[ai][m];
;                     if (gate) { v0 += b0; v1 += b1;
; #pragma unroll
;                         for (int e = 0; e < 4; ++e) { v0[e] = sigmoidf_(v0[e]); v1[e] = sigmoidf_(v1[e]); } }
;                     u32x4 w; w.x = pk2(v0[0], v0[1]); w.y = pk2(v0[2], v0[3]); w.z = pk2(v1[0], v1[1]); w.w = pk2(v1[2], v1[3]);
;                     if (s5c) *(GAS u32x4*)(ZS5 + ((size_t)(col >> 4) * M + (row0 + ai * HALF + m * 16)) * 16 + (col & 8)) = w;
;                     else *(GAS u32x4*)(Z + (size_t)(row0 + ai * HALF + m * 16) * ZP + col) = w;
; DI const LAS float* rstd_table(const Frame& F) {
;     ...
;         f32x4 t = (p[0] + p[1]) + (p[2] + p[3]) + ((p[4] + p[5]) + (p[6] + p[7]));
;         tab[r] = 1.f / sqrtf(((t[0] + t[1]) + (t[2] + t[3])) * (1.f / D) + NORM_EPS);
	v_mfma_f32_16x16x32_bf16 v[160:163], v[16:19], v[12:15], v[160:163]
	v_mfma_f32_16x16x32_bf16 v[164:167], v[20:23], v[12:15], v[164:167]
	s_waitcnt vmcnt(27)
	v_mfma_f32_16x16x32_bf16 v[160:163], v[28:31], v[24:27], v[160:163]
	v_mfma_f32_16x16x32_bf16 v[164:167], v[32:35], v[24:27], v[164:167]
	s_waitcnt vmcnt(24)
	v_mfma_f32_16x16x32_bf16 v[160:163], v[40:43], v[36:39], v[160:163]
	v_mfma_f32_16x16x32_bf16 v[164:167], v[44:47], v[36:39], v[164:167]
	s_waitcnt vmcnt(21)
	v_mfma_f32_16x16x32_bf16 v[160:163], v[52:55], v[48:51], v[160:163]
	v_mfma_f32_16x16x32_bf16 v[164:167], v[56:59], v[48:51], v[164:167]
	s_waitcnt vmcnt(18)
	v_mfma_f32_16x16x32_bf16 v[160:163], v[64:67], v[60:63], v[160:163]
	v_mfma_f32_16x16x32_bf16 v[164:167], v[68:71], v[60:63], v[164:167]
	s_waitcnt vmcnt(15)
	v_mfma_f32_16x16x32_bf16 v[160:163], v[76:79], v[72:75], v[160:163]
	v_mfma_f32_16x16x32_bf16 v[164:167], v[80:83], v[72:75], v[164:167]
	s_waitcnt vmcnt(12)
	v_mfma_f32_16x16x32_bf16 v[160:163], v[88:91], v[84:87], v[160:163]
	v_mfma_f32_16x16x32_bf16 v[164:167], v[92:95], v[84:87], v[164:167]
	s_waitcnt vmcnt(9)
	v_mfma_f32_16x16x32_bf16 v[160:163], v[100:103], v[96:99], v[160:163]
	v_mfma_f32_16x16x32_bf16 v[164:167], v[104:107], v[96:99], v[164:167]
	s_waitcnt vmcnt(6)
	v_mfma_f32_16x16x32_bf16 v[160:163], v[112:115], v[108:111], v[160:163]
	v_mfma_f32_16x16x32_bf16 v[164:167], v[116:119], v[108:111], v[164:167]
	s_waitcnt vmcnt(3)
	v_mfma_f32_16x16x32_bf16 v[160:163], v[124:127], v[120:123], v[160:163]
	v_mfma_f32_16x16x32_bf16 v[164:167], v[128:131], v[120:123], v[164:167]
	s_waitcnt vmcnt(0)
	v_mfma_f32_16x16x32_bf16 v[160:163], v[136:139], v[132:135], v[160:163]
	v_mfma_f32_16x16x32_bf16 v[164:167], v[140:143], v[132:135], v[164:167]
	v_pk_add_f32 v[206:207], v[206:207], v[210:211]
	v_pk_add_f32 v[204:205], v[204:205], v[208:209]
	v_pk_add_f32 v[198:199], v[198:199], v[202:203]
	v_pk_add_f32 v[196:197], v[196:197], v[200:201]
	v_pk_add_f32 v[198:199], v[206:207], v[198:199]
	v_pk_add_f32 v[196:197], v[204:205], v[196:197]
	v_pk_add_f32 v[200:201], v[222:223], v[236:237]
	v_pk_add_f32 v[202:203], v[220:221], v[234:235]
	v_pk_add_f32 v[204:205], v[214:215], v[218:219]
	v_pk_add_f32 v[206:207], v[212:213], v[216:217]
	v_pk_add_f32 v[200:201], v[200:201], v[204:205]
	v_pk_add_f32 v[202:203], v[202:203], v[206:207]
	v_pk_add_f32 v[198:199], v[198:199], v[200:201]
	v_pk_add_f32 v[196:197], v[196:197], v[202:203]
	s_nop 0
	v_pk_mov_b32 v[200:201], v[196:197], v[198:199] op_sel:[1,0]
	v_mov_b32_e32 v197, v199
	v_pk_add_f32 v[196:197], v[200:201], v[196:197]
	s_nop 0
	v_add_f32_e32 v196, v196, v197
	v_fmamk_f32 v196, v196, 0x3a000000, v225
	v_mul_f32_e32 v197, 0x4f800000, v196
	v_cmp_gt_f32_e32 vcc, 0xf800000, v196
	s_nop 1
	v_cndmask_b32_e32 v196, v196, v197, vcc
	v_sqrt_f32_e32 v197, v196
	s_nop 0
	v_add_u32_e32 v198, -1, v197
	v_fma_f32 v199, -v198, v197, v196
	v_cmp_ge_f32_e64 s[100:101], 0, v199
	v_add_u32_e32 v199, 1, v197
	s_nop 0
	v_cndmask_b32_e64 v198, v197, v198, s[100:101]
	v_fma_f32 v197, -v199, v197, v196
	v_cmp_lt_f32_e64 s[100:101], 0, v197
	s_nop 1
	v_cndmask_b32_e64 v197, v198, v199, s[100:101]
	v_mul_f32_e32 v198, 0x37800000, v197
	v_cndmask_b32_e32 v197, v197, v198, vcc
	v_cmp_class_f32_e32 vcc, v196, v226
	s_nop 1
	v_cndmask_b32_e32 v196, v197, v196, vcc
	v_div_scale_f32 v197, s[100:101], v196, v196, 1.0
	v_rcp_f32_e32 v198, v197
	s_nop 0
	v_fma_f32 v199, -v197, v198, 1.0
	v_fmac_f32_e32 v198, v199, v198
	v_div_scale_f32 v199, vcc, 1.0, v196, 1.0
	v_mul_f32_e32 v200, v199, v198
	v_fma_f32 v201, -v197, v200, v199
	v_fmac_f32_e32 v200, v201, v198
	v_fma_f32 v197, -v197, v200, v199
	v_div_fmas_f32 v197, v197, v198, v200
	v_div_fixup_f32 v196, v197, v196, 1.0
	s_nop 7
	v_mul_f32_e32 v160, v160, v196
	v_mul_f32_e32 v161, v161, v196
	v_mul_f32_e32 v162, v162, v196
	v_mul_f32_e32 v163, v163, v196
	v_mul_f32_e32 v164, v164, v196
	v_mul_f32_e32 v165, v165, v196
	v_mul_f32_e32 v166, v166, v196
	v_mul_f32_e32 v167, v167, v196
	v_cvt_pk_bf16_f32 v0, v160, v161
	v_cvt_pk_bf16_f32 v1, v162, v163
	v_cvt_pk_bf16_f32 v2, v164, v165
	v_cvt_pk_bf16_f32 v3, v166, v167
	global_store_dwordx2 v170, v[0:1], s[16:17]
	global_store_dwordx2 v170, v[2:3], s[6:7]

; #define GAS __attribute__((address_space(1)))
; DI void rwkv_fused_phase(const Frame& F, const CAS Args& a, int l) {
;     ...
;             for (int q = F.tid; q < 9 * 64; q += 512) { const int pi = q >> 6, i = q & 63; float val;
;                 if (pi < 3) val = mu[(pi == 0 ? ZC_R : (pi == 1 ? ZC_K : ZC_V)) - ZC_R + h * 64 + i];
;                 else if (pi == 3) val = a.in[16][(size_t)l * RW + h * 64 + i]; else if (pi == 4) val = a.in[18][(size_t)l * RW + h * 64 + i]; else if (pi == 5) val = a.in[20][(size_t)l * RW + h * 64 + i];
;                 else if (pi == 6) val = a.in[21][(size_t)l * RW + h * 64 + i]; else if (pi == 7) val = a.in[22][(size_t)l * RW + h * 64 + i];
;                 else val = (l > 0) ? a.in[28][(size_t)(l - 1) * RW + h * 64 + i] : 0.f;
;                 PRM[q] = val; }
;             f32x4 pvf[2], wl_[2]; u32x4 al_, vl_ = {0u, 0u, 0u, 0u};
;             { unsigned lro = (unsigned)((h * 64 + t) * 64 + 8 * cg); asm volatile("" : "+v"(lro));
;               wl_[0] = *(const GAS f32x4*)(LWp + lro); wl_[1] = *(const GAS f32x4*)(LWp + lro + 4);
;               unsigned lao = (unsigned)(((h * 2) * 64 + t) * 64 + 8 * cg); asm volatile("" : "+v"(lao));
;               al_ = *(const GAS u32x4*)(LAp + lao); if (l > 0) vl_ = *(const GAS u32x4*)(LAp + lao + 4096); }
; #pragma unroll
;             for (int q = 0; q < 2; ++q) pvf[q] = *(const GAS f32x4*)(P.VF + po + 4 * q);
; #pragma unroll
;             for (int which = 0; which < 3; ++which) { const int zc = (which == 0 ? ZC_R : (which == 1 ? ZC_K : ZC_V)) + ch;
;                 zc_[which] = *(const GAS u32x4*)(Z + (size_t)gr * ZP + zc); zp_[which] = *(const GAS u32x4*)(Z + (size_t)(gr > 0 ? gr - 1 : 0) * ZP + zc); }
.LBB0_627:
	s_lshl_b32 s20, s33, 14
	s_lshl_b32 s8, s33, 6
	v_lshl_add_u64 v[118:119], s[20:21], 0, v[64:65]
	v_or_b32_e32 v0, s8, v70
	v_lshl_or_b32 v120, v118, 6, v70
	v_or_b32_e32 v1, s8, v124
	v_add_u32_e32 v1, s8, v79
	v_lshl_or_b32 v184, v1, 6, v70
	v_mov_b32_e32 v60, 0
	v_lshl_add_u64 v[2:3], v[184:185], 2, s[12:13]
	v_lshl_add_u32 v184, s33, 13, v69
	global_load_dwordx4 v[12:15], v[2:3], off offset:16
	global_load_dwordx4 v[16:19], v[2:3], off
	s_and_b64 vcc, exec, s[44:45]
	v_lshl_add_u64 v[2:3], v[184:185], 1, s[24:25]
	global_load_dwordx4 v[8:11], v[2:3], off
	v_mov_b32_e32 v61, 0
	v_mov_b32_e32 v62, 0
	v_mov_b32_e32 v63, 0
	s_movk_i32 s20, 0x5ff
	s_cbranch_vccz .LBB0_657
	v_add_co_u32_e32 v2, vcc, 0x2000, v2
	s_nop 1
	v_addc_co_u32_e32 v3, vcc, 0, v3, vcc
	global_load_dwordx4 v[60:63], v[2:3], off
.LBB0_657:
	v_ashrrev_i32_e32 v1, 31, v0
	v_mov_b32_e32 v121, v185
	v_lshlrev_b64 v[0:1], 1, v[0:1]
	v_lshl_add_u64 v[122:123], v[120:121], 2, s[38:39]
	v_lshl_add_u64 v[2:3], v[66:67], 0, v[0:1]
	s_movk_i32 s0, 0x1000
	global_load_dwordx4 v[52:55], v[122:123], off offset:16
	global_load_dwordx4 v[56:59], v[122:123], off
	v_lshl_add_u64 v[0:1], v[116:117], 0, v[0:1]
	global_load_dwordx4 v[40:43], v[2:3], off offset:1536
	global_load_dwordx4 v[32:35], v[2:3], off offset:2816
	global_load_dwordx4 v[36:39], v[0:1], off offset:1536
	global_load_dwordx4 v[24:27], v[0:1], off offset:2816
	v_add_co_u32_e32 v2, vcc, s0, v2
	s_movk_i32 s60, 0x1000
	s_nop 0
	v_addc_co_u32_e32 v3, vcc, 0, v3, vcc
	v_add_co_u32_e32 v0, vcc, s0, v0
	s_nop 1
	v_addc_co_u32_e32 v1, vcc, 0, v1, vcc
	global_load_dwordx4 v[4:7], v[2:3], off
	global_load_dwordx4 v[188:191], v[0:1], off
	s_and_saveexec_b64 s[10:11], s[46:47]
	s_cbranch_execz .LBB0_655
	s_mov_b32 s9, s21
	s_lshl_b64 s[0:1], s[8:9], 2
	v_lshl_add_u64 v[44:45], v[80:81], 0, s[0:1]
	v_lshl_add_u64 v[46:47], v[82:83], 0, s[0:1]
	v_lshl_add_u64 v[48:49], v[84:85], 0, s[0:1]
	v_lshl_add_u64 v[50:51], v[86:87], 0, s[0:1]
	v_lshl_add_u64 v[28:29], v[88:89], 0, s[0:1]
	v_lshl_add_u64 v[30:31], v[90:91], 0, s[0:1]
	v_or_b32_e32 v196, s8, v128
	s_mov_b64 s[36:37], 0
	v_mov_b32_e32 v20, v176
	v_mov_b32_e32 v21, v74
	s_branch .LBB0_630
.LBB0_629:
	s_or_b64 exec, exec, s[0:1]
	s_waitcnt vmcnt(0)
	ds_write_b32 v20, v22
	v_add_u32_e32 v22, 0x200, v21
	v_cmp_lt_i32_e32 vcc, 63, v21
	v_add_u32_e32 v20, 0x800, v20
	s_or_b64 s[36:37], vcc, s[36:37]
	v_mov_b32_e32 v21, v22
	s_andn2_b64 exec, exec, s[36:37]
	s_cbranch_execz .LBB0_655
.LBB0_630:
	v_ashrrev_i32_e32 v23, 6, v21
	v_cmp_lt_i32_e32 vcc, 2, v23
	s_and_saveexec_b64 s[0:1], vcc
	s_xor_b64 s[16:17], exec, s[0:1]
	s_cbranch_execz .LBB0_653
	v_cmp_lt_i32_e32 vcc, 4, v23
	s_and_saveexec_b64 s[0:1], vcc
	s_xor_b64 s[14:15], exec, s[0:1]
	s_cbranch_execz .LBB0_646
	v_cmp_lt_i32_e32 vcc, 5, v23
	s_and_saveexec_b64 s[0:1], vcc
	s_xor_b64 s[0:1], exec, s[0:1]
	s_cbranch_execz .LBB0_643
	v_cmp_lt_i32_e32 vcc, 6, v23
	s_and_saveexec_b64 s[60:61], vcc
	s_xor_b64 s[60:61], exec, s[60:61]
	s_cbranch_execz .LBB0_640
	v_cmp_ne_u32_e32 vcc, 7, v23
	s_and_saveexec_b64 s[62:63], vcc
	s_xor_b64 s[62:63], exec, s[62:63]
	s_cbranch_execz .LBB0_637
	s_and_b64 vcc, exec, s[4:5]
	v_mov_b32_e32 v22, 0
	s_cbranch_vccnz .LBB0_637
	global_load_dword v22, v[30:31], off
.LBB0_637:
	s_andn2_saveexec_b64 s[62:63], s[62:63]
	s_cbranch_execz .LBB0_639
	global_load_dword v22, v[44:45], off

; DI void rwkv_fused_phase(const Frame& F, const CAS Args& a, int l) {
;     ...
;             for (int q = F.tid; q < 9 * 64; q += 512) { const int pi = q >> 6, i = q & 63; float val;
;                 if (pi < 3) val = mu[(pi == 0 ? ZC_R : (pi == 1 ? ZC_K : ZC_V)) - ZC_R + h * 64 + i];
;                 else if (pi == 3) val = a.in[16][(size_t)l * RW + h * 64 + i]; else if (pi == 4) val = a.in[18][(size_t)l * RW + h * 64 + i]; else if (pi == 5) val = a.in[20][(size_t)l * RW + h * 64 + i];
;                 else if (pi == 6) val = a.in[21][(size_t)l * RW + h * 64 + i]; else if (pi == 7) val = a.in[22][(size_t)l * RW + h * 64 + i];
;                 else val = (l > 0) ? a.in[28][(size_t)(l - 1) * RW + h * 64 + i] : 0.f;
;                 PRM[q] = val; }
.LBB0_640:
	s_andn2_saveexec_b64 s[60:61], s[60:61]
	s_cbranch_execz .LBB0_642
	global_load_dword v22, v[46:47], off

; DI void rwkv_fused_phase(const Frame& F, const CAS Args& a, int l) {
;     ...
;             for (int q = F.tid; q < 9 * 64; q += 512) { const int pi = q >> 6, i = q & 63; float val;
;                 if (pi < 3) val = mu[(pi == 0 ? ZC_R : (pi == 1 ? ZC_K : ZC_V)) - ZC_R + h * 64 + i];
;                 else if (pi == 3) val = a.in[16][(size_t)l * RW + h * 64 + i]; else if (pi == 4) val = a.in[18][(size_t)l * RW + h * 64 + i]; else if (pi == 5) val = a.in[20][(size_t)l * RW + h * 64 + i];
;                 else if (pi == 6) val = a.in[21][(size_t)l * RW + h * 64 + i]; else if (pi == 7) val = a.in[22][(size_t)l * RW + h * 64 + i];
;                 else val = (l > 0) ? a.in[28][(size_t)(l - 1) * RW + h * 64 + i] : 0.f;
;                 PRM[q] = val; }
.LBB0_643:
	s_andn2_saveexec_b64 s[0:1], s[0:1]
	s_cbranch_execz .LBB0_645
	global_load_dword v22, v[48:49], off

; DI void rwkv_fused_phase(const Frame& F, const CAS Args& a, int l) {
;     ...
;             for (int q = F.tid; q < 9 * 64; q += 512) { const int pi = q >> 6, i = q & 63; float val;
;                 if (pi < 3) val = mu[(pi == 0 ? ZC_R : (pi == 1 ? ZC_K : ZC_V)) - ZC_R + h * 64 + i];
;                 else if (pi == 3) val = a.in[16][(size_t)l * RW + h * 64 + i]; else if (pi == 4) val = a.in[18][(size_t)l * RW + h * 64 + i]; else if (pi == 5) val = a.in[20][(size_t)l * RW + h * 64 + i];
;                 else if (pi == 6) val = a.in[21][(size_t)l * RW + h * 64 + i]; else if (pi == 7) val = a.in[22][(size_t)l * RW + h * 64 + i];
;                 else val = (l > 0) ? a.in[28][(size_t)(l - 1) * RW + h * 64 + i] : 0.f;
;                 PRM[q] = val; }
.LBB0_646:
	s_andn2_saveexec_b64 s[0:1], s[14:15]
	s_cbranch_execz .LBB0_652
	v_cmp_lt_i32_e32 vcc, 3, v23
	s_and_saveexec_b64 s[14:15], vcc
	s_xor_b64 s[14:15], exec, s[14:15]
	s_cbranch_execz .LBB0_649
	global_load_dword v22, v[50:51], off
.LBB0_649:
	s_andn2_saveexec_b64 s[14:15], s[14:15]
	s_cbranch_execz .LBB0_651
	global_load_dword v22, v[28:29], off

; DI void unpack8(const u32x4 v, float (&f)[8]) { f[0] = bflo(v.x); f[1] = bfhi(v.x); f[2] = bflo(v.y); f[3] = bfhi(v.y); f[4] = bflo(v.z); f[5] = bfhi(v.z); f[6] = bflo(v.w); f[7] = bfhi(v.w); }
; DI void rwkv_fused_phase(const Frame& F, const CAS Args& a, int l) {
;     ...
;             for (int q = F.tid; q < 9 * 64; q += 512) { const int pi = q >> 6, i = q & 63; float val;
;                 if (pi < 3) val = mu[(pi == 0 ? ZC_R : (pi == 1 ? ZC_K : ZC_V)) - ZC_R + h * 64 + i];
;                 else if (pi == 3) val = a.in[16][(size_t)l * RW + h * 64 + i]; else if (pi == 4) val = a.in[18][(size_t)l * RW + h * 64 + i]; else if (pi == 5) val = a.in[20][(size_t)l * RW + h * 64 + i];
;                 else if (pi == 6) val = a.in[21][(size_t)l * RW + h * 64 + i]; else if (pi == 7) val = a.in[22][(size_t)l * RW + h * 64 + i];
;                 else val = (l > 0) ? a.in[28][(size_t)(l - 1) * RW + h * 64 + i] : 0.f;
;                 PRM[q] = val; }
;     ...
;               for (int which = 0; which < 3; ++which) { float cu[8], pr[8]; unpack8(zc_[which], cu); unpack8(zp_[which], pr);
; #pragma unroll
;                   for (int e = 0; e < 8; ++e) { const float pv = gr > 0 ? pr[e] : 0.f; const float mm = PRM[which * 64 + 8 * cg + e]; const float zs = cu[e] + (pv - cu[e]) * mm;
;                       if (which == 0) r[e] = zs; else if (which == 1) k[e] = zs; else v[e] = zs; } }
.LBB0_653:
	s_andn2_saveexec_b64 s[0:1], s[16:17]
	s_cbranch_execz .LBB0_629
	v_cmp_eq_u32_e32 vcc, 1, v23
	s_waitcnt vmcnt(0)
	s_nop 0
	v_cndmask_b32_e32 v22, v229, v230, vcc
	v_cmp_lt_u32_e32 vcc, 63, v21
	s_nop 1
	v_cndmask_b32_e32 v22, 0, v22, vcc
	v_add_u32_e32 v184, v22, v196
	v_lshl_add_u64 v[22:23], v[184:185], 2, s[22:23]
	global_load_dword v22, v[22:23], off
	s_branch .LBB0_629
.LBB0_655:
	s_or_b64 exec, exec, s[10:11]
	s_movk_i32 s60, 0x1000
	s_waitcnt vmcnt(0)
	v_lshlrev_b32_e32 v0, 16, v188
	v_and_b32_e32 v1, 0xffff0000, v188
	s_waitcnt lgkmcnt(0)
	s_barrier
	ds_read_b128 v[48:51], v135
	ds_read_b128 v[44:47], v135 offset:16
	ds_read_b128 v[28:31], v135 offset:256
	ds_read_b128 v[20:23], v135 offset:272
	v_cndmask_b32_e64 v199, 0, v1, s[6:7]
	v_cndmask_b32_e64 v198, 0, v0, s[6:7]
	ds_read_b128 v[0:3], v135 offset:512
	v_lshlrev_b32_e32 v196, 16, v4
	v_and_b32_e32 v197, 0xffff0000, v4
	v_pk_add_f32 v[198:199], v[198:199], v[196:197] neg_lo:[0,1] neg_hi:[0,1]
	v_lshlrev_b32_e32 v184, 16, v189
	v_and_b32_e32 v186, 0xffff0000, v189
	s_waitcnt lgkmcnt(0)
	v_pk_fma_f32 v[0:1], v[198:199], v[0:1], v[196:197]
	v_lshlrev_b32_e32 v4, 16, v5
	v_and_b32_e32 v5, 0xffff0000, v5
	v_cndmask_b32_e64 v189, 0, v186, s[6:7]
	v_cndmask_b32_e64 v188, 0, v184, s[6:7]
	ds_read_b128 v[196:199], v135 offset:528
	v_pk_add_f32 v[188:189], v[188:189], v[4:5] neg_lo:[0,1] neg_hi:[0,1]
	v_and_b32_e32 v184, 0xffff0000, v190
	v_pk_fma_f32 v[2:3], v[188:189], v[2:3], v[4:5]
	v_lshlrev_b32_e32 v4, 16, v6
	v_and_b32_e32 v5, 0xffff0000, v6
	v_lshlrev_b32_e32 v6, 16, v190
	v_cndmask_b32_e64 v189, 0, v184, s[6:7]
	v_cndmask_b32_e64 v188, 0, v6, s[6:7]
	v_pk_add_f32 v[188:189], v[188:189], v[4:5] neg_lo:[0,1] neg_hi:[0,1]
	v_lshlrev_b32_e32 v184, 16, v191
	v_and_b32_e32 v186, 0xffff0000, v191
	s_waitcnt lgkmcnt(0)
	v_pk_fma_f32 v[4:5], v[188:189], v[196:197], v[4:5]
	v_lshlrev_b32_e32 v6, 16, v7
	v_and_b32_e32 v7, 0xffff0000, v7
	v_cndmask_b32_e64 v189, 0, v186, s[6:7]
	v_cndmask_b32_e64 v188, 0, v184, s[6:7]
	v_pk_add_f32 v[188:189], v[188:189], v[6:7] neg_lo:[0,1] neg_hi:[0,1]
	s_nop 0
	v_pk_fma_f32 v[6:7], v[188:189], v[198:199], v[6:7]
	s_and_b64 vcc, exec, s[4:5]
	s_cbranch_vccnz .LBB0_659
	ds_read_b128 v[188:191], v135 offset:2048
	ds_read_b128 v[196:199], v135 offset:2064
	v_lshlrev_b32_e32 v184, 16, v60
	v_and_b32_e32 v60, 0xffff0000, v60
	v_lshlrev_b32_e32 v213, 16, v62
	v_and_b32_e32 v214, 0xffff0000, v62
	s_waitcnt lgkmcnt(1)
	v_add_f32_e32 v62, v188, v184
	v_add_f32_e32 v60, v189, v60
	v_mul_f32_e32 v62, 0xbfb8aa3b, v62
	v_mul_f32_e32 v60, 0xbfb8aa3b, v60
	v_exp_f32_e32 v62, v62
	v_exp_f32_e32 v184, v60
	v_lshlrev_b32_e32 v186, 16, v61
	v_and_b32_e32 v61, 0xffff0000, v61
	v_lshlrev_b32_e32 v215, 16, v63
	v_and_b32_e32 v189, 0xffff0000, v63
	v_add_f32_e32 v63, v190, v186
	v_add_f32_e32 v61, v191, v61
	v_mul_f32_e32 v63, 0xbfb8aa3b, v63
	v_mul_f32_e32 v61, 0xbfb8aa3b, v61
	v_add_f32_e32 v60, 1.0, v62
	v_add_f32_e32 v62, 1.0, v184
	v_exp_f32_e32 v63, v63
	v_exp_f32_e32 v184, v61
	v_rcp_f32_e32 v61, v62
	s_waitcnt lgkmcnt(0)
	v_add_f32_e32 v186, v197, v214
	v_add_f32_e32 v62, 1.0, v63
	v_add_f32_e32 v63, 1.0, v184
	v_add_f32_e32 v184, v196, v213
	v_mul_f32_e32 v184, 0xbfb8aa3b, v184
	v_exp_f32_e32 v184, v184
	v_mul_f32_e32 v186, 0xbfb8aa3b, v186
	v_exp_f32_e32 v186, v186
	v_add_f32_e32 v189, v199, v189
	v_add_f32_e32 v184, 1.0, v184
	v_rcp_f32_e32 v188, v184
	v_add_f32_e32 v184, 1.0, v186
	v_add_f32_e32 v186, v198, v215
	v_mul_f32_e32 v186, 0xbfb8aa3b, v186
	v_exp_f32_e32 v186, v186
	v_mul_f32_e32 v189, 0xbfb8aa3b, v189
	v_exp_f32_e32 v191, v189
	v_rcp_f32_e32 v189, v184
	v_add_f32_e32 v184, 1.0, v186
	v_rcp_f32_e32 v190, v184
	v_add_f32_e32 v184, 1.0, v191
	v_rcp_f32_e32 v60, v60
	v_rcp_f32_e32 v62, v62
	v_rcp_f32_e32 v63, v63
	v_rcp_f32_e32 v191, v184
	v_sub_f32_e32 v57, v57, v1
	v_sub_f32_e32 v56, v56, v0
	v_sub_f32_e32 v59, v59, v3
	v_sub_f32_e32 v58, v58, v2
	v_sub_f32_e32 v53, v53, v5
	v_sub_f32_e32 v52, v52, v4
	v_sub_f32_e32 v55, v55, v7
	v_sub_f32_e32 v54, v54, v6
	v_pk_fma_f32 v[2:3], v[58:59], v[62:63], v[2:3]
	v_pk_fma_f32 v[0:1], v[56:57], v[60:61], v[0:1]
	v_pk_fma_f32 v[6:7], v[54:55], v[190:191], v[6:7]
	v_pk_fma_f32 v[4:5], v[52:53], v[188:189], v[4:5]

; DI int lane_id_fresh() { int l; asm volatile("v_mbcnt_lo_u32_b32 %0, -1, 0\n\tv_mbcnt_hi_u32_b32 %0, -1, %0" : "=v"(l)); return l; }
; __device__ __forceinline__ unsigned xb_add(unsigned* p, unsigned v) { return __hip_atomic_fetch_add(p, v, __ATOMIC_RELAXED, __HIP_MEMORY_SCOPE_AGENT); }
; __device__ __forceinline__ void xcd_barrier(const XcdBarrier& b) {
;     asm volatile("s_waitcnt vmcnt(0)" ::: "memory");
;     __syncthreads();
;     if (b.w0 && lane_id_fresh() == 0) {
;         unsigned* bar = b.bar;
;         __builtin_amdgcn_s_waitcnt(0);
;         unsigned nloc = b.st[0], nx = b.st[1];
;         if (nloc == 0u) { xcd_barrier_complete(bar, b.x, nloc, nx); b.st[0] = nloc; b.st[1] = nx; }
;         const unsigned old = xb_add(&bar[XB_XSUB(b.x)], 1u);
;         const unsigned gen = old / nloc;
;         if (old + 1u == (gen + 1u) * nloc) {
.LBB0_1031:
	v_readlane_b32 s0, v254, 37
	s_add_i32 s17, s0, 7
	s_waitcnt lgkmcnt(0)
	v_readlane_b32 s0, v252, 10
	v_readlane_b32 s3, v252, 13
	s_cmp_ge_i32 s17, s3
	v_readlane_b32 s1, v252, 11
	v_readlane_b32 s2, v252, 12
	s_cbranch_scc1 .LBB0_1083
	s_waitcnt vmcnt(0)
	v_readlane_b32 s0, v252, 5
	v_readlane_b32 s1, v252, 6
	s_and_b64 vcc, exec, s[0:1]
	s_barrier
	s_cbranch_vccnz .LBB0_1082
	v_mbcnt_lo_u32_b32 v0, -1, 0
	v_mbcnt_hi_u32_b32 v0, -1, v0
	s_nop 0
	v_cmp_eq_u32_e32 vcc, 0, v0
	s_and_saveexec_b64 s[2:3], vcc
	s_cbranch_execz .LBB0_1081
	v_readlane_b32 s0, v254, 5
	s_waitcnt vmcnt(0) expcnt(0) lgkmcnt(0)
	s_nop 0
	v_mov_b32_e32 v0, s0
	ds_read_b32 v2, v0
	v_readlane_b32 s0, v254, 6
	s_waitcnt lgkmcnt(0)
	v_cmp_ne_u32_e32 vcc, 0, v2
	v_mov_b32_e32 v0, s0
	ds_read_b32 v0, v0
	s_cbranch_vccnz .LBB0_1049
	v_readlane_b32 s4, v252, 7
	v_readlane_b32 s5, v252, 8
	s_load_dwordx2 s[0:1], s[4:5], 0x4
	s_mov_b32 s9, 1
	s_waitcnt lgkmcnt(0)
	s_mul_i32 s8, s0, s16
	s_mul_i32 s8, s8, s1
	s_branch .LBB0_1037

; #define FRAME() const CAS Args* ap; const Frame F = make_frame(lds, ap, wv); const CAS Args& A = *ap; (void)A
; __device__ __forceinline__ void xcd_barrier(const XcdBarrier& b) {
;     ...
;     __syncthreads();
; __global__ void __launch_bounds__(512, 2) trunk_fwd(Args args_unused) {
;     ...
;         if (PHEN(7) && IN(s0 + 7)) { FRAME();
.LBB0_1082:
	s_waitcnt lgkmcnt(0)
	s_barrier
.LBB0_1083:
	v_readlane_b32 s0, v252, 10
	v_readlane_b32 s2, v252, 12
	v_readlane_b32 s1, v252, 11
	v_readlane_b32 s3, v252, 13
	s_cmp_le_i32 s2, s17
	s_cselect_b64 s[0:1], -1, 0
	s_cmp_lt_i32 s17, s3
	s_cselect_b64 s[2:3], -1, 0
	s_and_b64 s[2:3], s[0:1], s[2:3]
	s_mov_b64 s[0:1], -1
	s_and_b64 vcc, exec, s[2:3]
	s_cbranch_vccnz .LBB0_1085
	v_readlane_b32 s0, v254, 37
	s_add_i32 s17, s0, 8
	s_mov_b64 s[0:1], 0

; #define GAS __attribute__((address_space(1)))
; #define SB() __builtin_amdgcn_sched_barrier(0)
; DI const LAS float* rstd_table(const Frame& F) {
;     ...
;     for (int r = F.tid; r < 2048; r += 512) { f32x4 p[8];
; #pragma unroll
;         for (int q = 0; q < 8; ++q) p[q] = ((const GAS f32x4*)(P + (size_t)r * 32))[q];
;         SB();
;         f32x4 t = (p[0] + p[1]) + (p[2] + p[3]) + ((p[4] + p[5]) + (p[6] + p[7]));
;         tab[r] = 1.f / sqrtf(((t[0] + t[1]) + (t[2] + t[3])) * (1.f / D) + NORM_EPS);
;         SB(); }
.LBB0_1379:
	v_lshl_add_u64 v[132:133], v[0:1], 0, s[14:15]
	v_lshl_add_u64 v[134:135], v[132:133], 0, s[14:15]
	v_lshl_add_u64 v[136:137], v[134:135], 0, s[14:15]
	global_load_dwordx4 v[4:7], v[0:1], off offset:32
	global_load_dwordx4 v[8:11], v[0:1], off offset:48
	global_load_dwordx4 v[12:15], v[0:1], off
	global_load_dwordx4 v[16:19], v[0:1], off offset:16
	global_load_dwordx4 v[20:23], v[0:1], off offset:96
	global_load_dwordx4 v[24:27], v[0:1], off offset:112
	global_load_dwordx4 v[28:31], v[0:1], off offset:64
	global_load_dwordx4 v[32:35], v[0:1], off offset:80
	global_load_dwordx4 v[36:39], v[132:133], off offset:32
	global_load_dwordx4 v[40:43], v[132:133], off offset:48
	global_load_dwordx4 v[44:47], v[132:133], off
	global_load_dwordx4 v[48:51], v[132:133], off offset:16
	global_load_dwordx4 v[52:55], v[132:133], off offset:96
	global_load_dwordx4 v[56:59], v[132:133], off offset:112
	global_load_dwordx4 v[60:63], v[132:133], off offset:64
	global_load_dwordx4 v[64:67], v[132:133], off offset:80
	global_load_dwordx4 v[68:71], v[134:135], off offset:32
	global_load_dwordx4 v[72:75], v[134:135], off offset:48
	global_load_dwordx4 v[76:79], v[134:135], off
	global_load_dwordx4 v[80:83], v[134:135], off offset:16
	global_load_dwordx4 v[84:87], v[134:135], off offset:96
	global_load_dwordx4 v[88:91], v[134:135], off offset:112
	global_load_dwordx4 v[92:95], v[134:135], off offset:64
	global_load_dwordx4 v[96:99], v[134:135], off offset:80
	global_load_dwordx4 v[100:103], v[136:137], off offset:32
	global_load_dwordx4 v[104:107], v[136:137], off offset:48
	global_load_dwordx4 v[108:111], v[136:137], off
	global_load_dwordx4 v[112:115], v[136:137], off offset:16
	global_load_dwordx4 v[116:119], v[136:137], off offset:96
	global_load_dwordx4 v[120:123], v[136:137], off offset:112
	global_load_dwordx4 v[124:127], v[136:137], off offset:64
	global_load_dwordx4 v[128:131], v[136:137], off offset:80
	s_waitcnt vmcnt(28)
	v_pk_add_f32 v[14:15], v[14:15], v[18:19]
	v_pk_add_f32 v[12:13], v[12:13], v[16:17]
	v_pk_add_f32 v[6:7], v[6:7], v[10:11]
	v_pk_add_f32 v[4:5], v[4:5], v[8:9]
	v_pk_add_f32 v[6:7], v[14:15], v[6:7]
	v_pk_add_f32 v[4:5], v[12:13], v[4:5]
	s_waitcnt vmcnt(24)
	v_pk_add_f32 v[8:9], v[30:31], v[34:35]
	v_pk_add_f32 v[10:11], v[28:29], v[32:33]
	v_pk_add_f32 v[12:13], v[22:23], v[26:27]
	v_pk_add_f32 v[14:15], v[20:21], v[24:25]
	v_pk_add_f32 v[8:9], v[8:9], v[12:13]
	v_pk_add_f32 v[10:11], v[10:11], v[14:15]
	v_pk_add_f32 v[6:7], v[6:7], v[8:9]
	v_pk_add_f32 v[4:5], v[4:5], v[10:11]
	s_nop 0
	v_pk_mov_b32 v[8:9], v[4:5], v[6:7] op_sel:[1,0]
	v_mov_b32_e32 v5, v7
	v_pk_add_f32 v[4:5], v[8:9], v[4:5]
	s_nop 0
	v_add_f32_e32 v4, v4, v5
	v_fmamk_f32 v4, v4, 0x3a000000, v225
	v_mul_f32_e32 v5, 0x4f800000, v4
	v_cmp_gt_f32_e32 vcc, s43, v4
	s_nop 1
	v_cndmask_b32_e32 v4, v4, v5, vcc
	v_sqrt_f32_e32 v5, v4
	s_nop 0
	v_add_u32_e32 v6, -1, v5
	v_fma_f32 v7, -v6, v5, v4
	v_cmp_ge_f32_e64 s[4:5], 0, v7
	v_add_u32_e32 v7, 1, v5
	s_nop 0
	v_cndmask_b32_e64 v6, v5, v6, s[4:5]
	v_fma_f32 v5, -v7, v5, v4
	v_cmp_lt_f32_e64 s[4:5], 0, v5
	s_nop 1
	v_cndmask_b32_e64 v5, v6, v7, s[4:5]
	v_mul_f32_e32 v6, 0x37800000, v5
	v_cndmask_b32_e32 v5, v5, v6, vcc
	v_cmp_class_f32_e32 vcc, v4, v226
	s_nop 1
	v_cndmask_b32_e32 v4, v5, v4, vcc
	v_div_scale_f32 v5, s[0:1], v4, v4, 1.0
	v_rcp_f32_e32 v6, v5
	s_nop 0
	v_fma_f32 v7, -v5, v6, 1.0
	v_fmac_f32_e32 v6, v7, v6
	v_div_scale_f32 v7, vcc, 1.0, v4, 1.0
	v_mul_f32_e32 v8, v7, v6
	v_fma_f32 v9, -v5, v8, v7
	v_fmac_f32_e32 v8, v9, v6
	v_fma_f32 v5, -v5, v8, v7
	v_div_fmas_f32 v5, v5, v6, v8
	v_div_fixup_f32 v4, v5, v4, 1.0
	ds_write_b32 v3, v4
	s_waitcnt vmcnt(20)
	v_pk_add_f32 v[46:47], v[46:47], v[50:51]
	v_pk_add_f32 v[44:45], v[44:45], v[48:49]
	v_pk_add_f32 v[38:39], v[38:39], v[42:43]
	v_pk_add_f32 v[36:37], v[36:37], v[40:41]
	v_pk_add_f32 v[38:39], v[46:47], v[38:39]
	v_pk_add_f32 v[36:37], v[44:45], v[36:37]
	s_waitcnt vmcnt(16)
; #define GAS __attribute__((address_space(1)))
; #define SB() __builtin_amdgcn_sched_barrier(0)
; DI const LAS float* rstd_table(const Frame& F) {
;     ...
;     for (int r = F.tid; r < 2048; r += 512) { f32x4 p[8];
; #pragma unroll
;         for (int q = 0; q < 8; ++q) p[q] = ((const GAS f32x4*)(P + (size_t)r * 32))[q];
;         SB();
;         f32x4 t = (p[0] + p[1]) + (p[2] + p[3]) + ((p[4] + p[5]) + (p[6] + p[7]));
;         tab[r] = 1.f / sqrtf(((t[0] + t[1]) + (t[2] + t[3])) * (1.f / D) + NORM_EPS);
;         SB(); }
	v_pk_add_f32 v[40:41], v[62:63], v[66:67]
	v_pk_add_f32 v[42:43], v[60:61], v[64:65]
	v_pk_add_f32 v[44:45], v[54:55], v[58:59]
	v_pk_add_f32 v[46:47], v[52:53], v[56:57]
	v_pk_add_f32 v[40:41], v[40:41], v[44:45]
	v_pk_add_f32 v[42:43], v[42:43], v[46:47]
	v_pk_add_f32 v[38:39], v[38:39], v[40:41]
	v_pk_add_f32 v[36:37], v[36:37], v[42:43]
	s_nop 0
	v_pk_mov_b32 v[40:41], v[36:37], v[38:39] op_sel:[1,0]
	v_mov_b32_e32 v37, v39
	v_pk_add_f32 v[36:37], v[40:41], v[36:37]
	s_nop 0
	v_add_f32_e32 v36, v36, v37
	v_fmamk_f32 v36, v36, 0x3a000000, v225
	v_mul_f32_e32 v37, 0x4f800000, v36
	v_cmp_gt_f32_e32 vcc, s43, v36
	s_nop 1
	v_cndmask_b32_e32 v36, v36, v37, vcc
	v_sqrt_f32_e32 v37, v36
	s_nop 0
	v_add_u32_e32 v38, -1, v37
	v_fma_f32 v39, -v38, v37, v36
	v_cmp_ge_f32_e64 s[4:5], 0, v39
	v_add_u32_e32 v39, 1, v37
	s_nop 0
	v_cndmask_b32_e64 v38, v37, v38, s[4:5]
	v_fma_f32 v37, -v39, v37, v36
	v_cmp_lt_f32_e64 s[4:5], 0, v37
	s_nop 1
	v_cndmask_b32_e64 v37, v38, v39, s[4:5]
	v_mul_f32_e32 v38, 0x37800000, v37
	v_cndmask_b32_e32 v37, v37, v38, vcc
	v_cmp_class_f32_e32 vcc, v36, v226
	s_nop 1
	v_cndmask_b32_e32 v36, v37, v36, vcc
	v_div_scale_f32 v37, s[0:1], v36, v36, 1.0
	v_rcp_f32_e32 v38, v37
	s_nop 0
	v_fma_f32 v39, -v37, v38, 1.0
	v_fmac_f32_e32 v38, v39, v38
	v_div_scale_f32 v39, vcc, 1.0, v36, 1.0
	v_mul_f32_e32 v40, v39, v38
	v_fma_f32 v41, -v37, v40, v39
	v_fmac_f32_e32 v40, v41, v38
	v_fma_f32 v37, -v37, v40, v39
	v_div_fmas_f32 v37, v37, v38, v40
	v_div_fixup_f32 v36, v37, v36, 1.0
	ds_write_b32 v3, v36 offset:2048
	s_waitcnt vmcnt(12)
	v_pk_add_f32 v[78:79], v[78:79], v[82:83]
	v_pk_add_f32 v[76:77], v[76:77], v[80:81]
	v_pk_add_f32 v[70:71], v[70:71], v[74:75]
	v_pk_add_f32 v[68:69], v[68:69], v[72:73]
	v_pk_add_f32 v[70:71], v[78:79], v[70:71]
	v_pk_add_f32 v[68:69], v[76:77], v[68:69]
	s_waitcnt vmcnt(8)
	v_pk_add_f32 v[72:73], v[94:95], v[98:99]
	v_pk_add_f32 v[74:75], v[92:93], v[96:97]
	v_pk_add_f32 v[76:77], v[86:87], v[90:91]
	v_pk_add_f32 v[78:79], v[84:85], v[88:89]
	v_pk_add_f32 v[72:73], v[72:73], v[76:77]
	v_pk_add_f32 v[74:75], v[74:75], v[78:79]
	v_pk_add_f32 v[70:71], v[70:71], v[72:73]
	v_pk_add_f32 v[68:69], v[68:69], v[74:75]
	s_nop 0
	v_pk_mov_b32 v[72:73], v[68:69], v[70:71] op_sel:[1,0]
	v_mov_b32_e32 v69, v71
	v_pk_add_f32 v[68:69], v[72:73], v[68:69]
	s_nop 0
	v_add_f32_e32 v68, v68, v69
	v_fmamk_f32 v68, v68, 0x3a000000, v225
	v_mul_f32_e32 v69, 0x4f800000, v68
	v_cmp_gt_f32_e32 vcc, s43, v68
	s_nop 1
	v_cndmask_b32_e32 v68, v68, v69, vcc
	v_sqrt_f32_e32 v69, v68
	s_nop 0
	v_add_u32_e32 v70, -1, v69
	v_fma_f32 v71, -v70, v69, v68
	v_cmp_ge_f32_e64 s[4:5], 0, v71
	v_add_u32_e32 v71, 1, v69
	s_nop 0
	v_cndmask_b32_e64 v70, v69, v70, s[4:5]
	v_fma_f32 v69, -v71, v69, v68
	v_cmp_lt_f32_e64 s[4:5], 0, v69
	s_nop 1
	v_cndmask_b32_e64 v69, v70, v71, s[4:5]
	v_mul_f32_e32 v70, 0x37800000, v69
	v_cndmask_b32_e32 v69, v69, v70, vcc
	v_cmp_class_f32_e32 vcc, v68, v226
	s_nop 1
	v_cndmask_b32_e32 v68, v69, v68, vcc
	v_div_scale_f32 v69, s[0:1], v68, v68, 1.0
	v_rcp_f32_e32 v70, v69
	s_nop 0
	v_fma_f32 v71, -v69, v70, 1.0
	v_fmac_f32_e32 v70, v71, v70
	v_div_scale_f32 v71, vcc, 1.0, v68, 1.0
	v_mul_f32_e32 v72, v71, v70
	v_fma_f32 v73, -v69, v72, v71
	v_fmac_f32_e32 v72, v73, v70
	v_fma_f32 v69, -v69, v72, v71
	v_div_fmas_f32 v69, v69, v70, v72
	v_div_fixup_f32 v68, v69, v68, 1.0
	ds_write_b32 v3, v68 offset:4096
	s_waitcnt vmcnt(4)
	v_pk_add_f32 v[110:111], v[110:111], v[114:115]
	v_pk_add_f32 v[108:109], v[108:109], v[112:113]
	v_pk_add_f32 v[102:103], v[102:103], v[106:107]
	v_pk_add_f32 v[100:101], v[100:101], v[104:105]
	v_pk_add_f32 v[102:103], v[110:111], v[102:103]
	v_pk_add_f32 v[100:101], v[108:109], v[100:101]
	s_waitcnt vmcnt(0)
	v_pk_add_f32 v[104:105], v[126:127], v[130:131]
	v_pk_add_f32 v[106:107], v[124:125], v[128:129]
	v_pk_add_f32 v[108:109], v[118:119], v[122:123]
	v_pk_add_f32 v[110:111], v[116:117], v[120:121]
	v_pk_add_f32 v[104:105], v[104:105], v[108:109]
	v_pk_add_f32 v[106:107], v[106:107], v[110:111]
	v_pk_add_f32 v[102:103], v[102:103], v[104:105]
	v_pk_add_f32 v[100:101], v[100:101], v[106:107]
	s_nop 0
	v_pk_mov_b32 v[104:105], v[100:101], v[102:103] op_sel:[1,0]
	v_mov_b32_e32 v101, v103
	v_pk_add_f32 v[100:101], v[104:105], v[100:101]
	s_nop 0
	v_add_f32_e32 v100, v100, v101
	v_fmamk_f32 v100, v100, 0x3a000000, v225
	v_mul_f32_e32 v101, 0x4f800000, v100
	v_cmp_gt_f32_e32 vcc, s43, v100
	s_nop 1
	v_cndmask_b32_e32 v100, v100, v101, vcc
	v_sqrt_f32_e32 v101, v100
	s_nop 0
	v_add_u32_e32 v102, -1, v101
	v_fma_f32 v103, -v102, v101, v100
	v_cmp_ge_f32_e64 s[4:5], 0, v103
	v_add_u32_e32 v103, 1, v101
	s_nop 0
	v_cndmask_b32_e64 v102, v101, v102, s[4:5]
	v_fma_f32 v101, -v103, v101, v100
	v_cmp_lt_f32_e64 s[4:5], 0, v101
	s_nop 1
	v_cndmask_b32_e64 v101, v102, v103, s[4:5]
	v_mul_f32_e32 v102, 0x37800000, v101
	v_cndmask_b32_e32 v101, v101, v102, vcc
	v_cmp_class_f32_e32 vcc, v100, v226
	s_nop 1
	v_cndmask_b32_e32 v100, v101, v100, vcc
	v_div_scale_f32 v101, s[0:1], v100, v100, 1.0
	v_rcp_f32_e32 v102, v101
	s_nop 0
	v_fma_f32 v103, -v101, v102, 1.0
	v_fmac_f32_e32 v102, v103, v102
	v_div_scale_f32 v103, vcc, 1.0, v100, 1.0
	v_mul_f32_e32 v104, v103, v102
	v_fma_f32 v105, -v101, v104, v103
	v_fmac_f32_e32 v104, v105, v102
	v_fma_f32 v101, -v101, v104, v103
	v_div_fmas_f32 v101, v101, v102, v104
	v_div_fixup_f32 v100, v101, v100, 1.0
	ds_write_b32 v3, v100 offset:6144

; __global__ void __launch_bounds__(512, 2) trunk_fwd(Args args_unused) {
	.amdhsa_kernel _Z9trunk_fwd4Args
		.amdhsa_group_segment_fixed_size 0
		.amdhsa_private_segment_fixed_size 0
		.amdhsa_kernarg_size 584
		.amdhsa_user_sgpr_count 2
		.amdhsa_user_sgpr_dispatch_ptr 0
		.amdhsa_user_sgpr_queue_ptr 0
		.amdhsa_user_sgpr_kernarg_segment_ptr 1
		.amdhsa_user_sgpr_dispatch_id 0
		.amdhsa_user_sgpr_kernarg_preload_length 0
		.amdhsa_user_sgpr_kernarg_preload_offset 0
		.amdhsa_user_sgpr_private_segment_size 0
		.amdhsa_uses_dynamic_stack 0
		.amdhsa_enable_private_segment 0
		.amdhsa_system_sgpr_workgroup_id_x 1
		.amdhsa_system_sgpr_workgroup_id_y 0
		.amdhsa_system_sgpr_workgroup_id_z 0
		.amdhsa_system_sgpr_workgroup_info 0
		.amdhsa_system_vgpr_workitem_id 0
		.amdhsa_next_free_vgpr 256
		.amdhsa_next_free_sgpr 102
		.amdhsa_accum_offset 256
		.amdhsa_reserve_vcc 1
		.amdhsa_float_round_mode_32 0
		.amdhsa_float_round_mode_16_64 0
		.amdhsa_float_denorm_mode_32 3
		.amdhsa_float_denorm_mode_16_64 3
		.amdhsa_dx10_clamp 1
		.amdhsa_ieee_mode 1
		.amdhsa_fp16_overflow 0
		.amdhsa_tg_split 0
		.amdhsa_exception_fp_ieee_invalid_op 0
		.amdhsa_exception_fp_denorm_src 0
		.amdhsa_exception_fp_ieee_div_zero 0
		.amdhsa_exception_fp_ieee_overflow 0
		.amdhsa_exception_fp_ieee_underflow 0
		.amdhsa_exception_fp_ieee_inexact 0
		.amdhsa_exception_int_div_zero 0
	.end_amdhsa_kernel

; __global__ void __launch_bounds__(512, 2) trunk_fwd(Args args_unused) {
amdhsa.kernels:
  - .agpr_count:     0
    .args:
      - .offset:         0
        .size:           328
        .value_kind:     by_value
      - .offset:         328
        .size:           4
        .value_kind:     hidden_block_count_x
      - .offset:         332
        .size:           4
        .value_kind:     hidden_block_count_y
      - .offset:         336
        .size:           4
        .value_kind:     hidden_block_count_z
      - .offset:         340
        .size:           2
        .value_kind:     hidden_group_size_x
      - .offset:         342
        .size:           2
        .value_kind:     hidden_group_size_y
      - .offset:         344
        .size:           2
        .value_kind:     hidden_group_size_z
      - .offset:         346
        .size:           2
        .value_kind:     hidden_remainder_x
      - .offset:         348
        .size:           2
        .value_kind:     hidden_remainder_y
      - .offset:         350
        .size:           2
        .value_kind:     hidden_remainder_z
      - .offset:         368
        .size:           8
        .value_kind:     hidden_global_offset_x
      - .offset:         376
        .size:           8
        .value_kind:     hidden_global_offset_y
      - .offset:         384
        .size:           8
        .value_kind:     hidden_global_offset_z
      - .offset:         392
        .size:           2
        .value_kind:     hidden_grid_dims
      - .offset:         448
        .size:           4
        .value_kind:     hidden_dynamic_lds_size
    .group_segment_fixed_size: 0
    .kernarg_segment_align: 8
    .kernarg_segment_size: 584
    .language:       OpenCL C
    .language_version:
      - 2
      - 0
    .max_flat_workgroup_size: 512
    .name:           _Z9trunk_fwd4Args
    .private_segment_fixed_size: 0
    .sgpr_count:     108
    .sgpr_spill_count: 209
    .symbol:         _Z9trunk_fwd4Args.kd
    .uniform_work_group_size: 1
    .uses_dynamic_stack: false
    .vgpr_count:     256
    .vgpr_spill_count: 0
    .wavefront_size: 64
